# combination of the three instruction-diet edits on the best kernel: first K iteration peeled with C=0 (no accumulator clear), DPP folded into FMAC in the ffn epilogue, redundant setprio pairs removed
# baseline (speedup 1.0000x reference)
; #define PG8_STAGE(bufoff, gbase, voff) do { _Pragma("unroll") for (int _i = 0; _i < 2; ++_i) \
;         __builtin_amdgcn_global_load_lds((const unsigned*)((const char*)(gbase) + (voff)[_i]), (PG8_LAS unsigned*)(lds + (bufoff) + ldsw + _i * 8192), 16, 0, 0); } while (0)
; #define PG8_LDA(dst, b, h) do { _Pragma("unroll") for (int m = 0; m < 4; ++m) _Pragma("unroll") for (int k = 0; k < 2; ++k) dst[m][k] = *(const PG8_LAS bf16x8*)(lds + PG8_SA(b, h) + aoff + m * 2048 + k * 1024); } while (0)
; #define PG8_WAIT_V(n) asm volatile("s_waitcnt vmcnt(" #n ")" ::: "memory")
; template <class Epi, class Sched, bool ALIGN_EPI = false, bool SP2 = false>
; __device__ __forceinline__ void gemm_phase(PG8_LAS unsigned char* lds, const Gemm g, const Sched& S, const Epi& E, int tid_in) {
;     ...
;     f32x4 acc[2][2][4][2];
; #pragma unroll
;     for (int a = 0; a < 2; ++a)
; #pragma unroll
;         for (int b = 0; b < 2; ++b)
; #pragma unroll
;             for (int m = 0; m < 4; ++m)
; #pragma unroll
;                 for (int n = 0; n < 2; ++n) acc[a][b][m][n] = (f32x4){0.f, 0.f, 0.f, 0.f};
;     ...
;     for (;;) {
;         const bool has_next = S.next(ui + 1, nxt);
;         const char* nA = has_next ? (const char*)g.A + (size_t)nxt.pm * tstepA + (size_t)PG8_KOFF(nxt.pn) * kstep : cA; const char* nB = has_next ? (const char*)g.Bt + (size_t)nxt.pn * tstep + (size_t)PG8_KOFF(nxt.pn) * kstep : cB;
;         for (int t = 0; t < ntc; t += 2) {
;             const bool last = (t == ntc - 2);
;             const char* a1 = PG8_KA(cA, t + 1);
;             const char* a2 = last ? nA : PG8_KA(cA, t + 2); const char* b2 = last ? nB : cB + (size_t)(t + 2) * kstep;
;             const char* a3 = last ? PG8_KA(nA, 1) : PG8_KA(cA, t + 3); const char* b3 = b2 + kstep;
;             if (last && has_next) S.a_ready(nxt);
;             if constexpr (SP2) {
;             PG8_LDB(B0, 0, 0); PG8_LDB(B1, 0, 1); PG8_SCHED; PG8_LDA(At, 0, 0); PG8_STAGE(PG8_SA(1, 1), a1 + hstepA, voffA);
;             PG8_WAIT_V(8); PG8_WAIT_L(0); PG8_BAR; PG8_MMA(0, 0, At, B0); PG8_MMA(0, 1, At, B1); PG8_BAR; PG8_SCHED;
;             PG8_LDA(At, 0, 1); PG8_STAGE(PG8_SB(0, 0), b2, voffB); PG8_STAGE(PG8_SB(0, 1), b2 + hstep, voffB); PG8_STAGE(PG8_SA(0, 0), a2, voffA);
;             PG8_WAIT_V(8); PG8_WAIT_L(0); PG8_BAR; PG8_MMA(1, 0, At, B0); PG8_MMA(1, 1, At, B1); PG8_BAR; PG8_SCHED;
.LBB0_605:
	s_add_u32 s18, s40, 0x80
	s_addc_u32 s19, s41, 0
	s_add_u32 s20, s10, 0x100
	s_addc_u32 s21, s11, 0
	s_add_u32 s0, s2, 0x80
	s_addc_u32 s1, s3, 0
	s_waitcnt lgkmcnt(0)
	v_lshl_add_u64 v[130:131], s[0:1], 0, v[206:207]
	v_lshl_add_u64 v[132:133], s[0:1], 0, v[208:209]
	s_lshl_b64 s[0:1], s[94:95], 7
	s_add_u32 s22, s0, 0xffffff00
	s_mov_b32 s10, 0
	s_mov_b64 s[0:1], 0
	s_waitcnt vmcnt(0)
	s_or_b32 s11, s10, 1
	s_cmp_ge_u32 s11, s84
	s_cselect_b32 s27, s86, 0
	s_cselect_b32 s79, s85, 0
	s_add_i32 s23, s10, 2
	s_cmp_ge_u32 s23, s84
	s_cselect_b32 s44, s86, 0
	s_cselect_b32 s11, s85, 0
	s_add_u32 s44, s44, s0
	s_addc_u32 s11, s11, s1
	s_add_u32 s44, s2, s44
	s_addc_u32 s11, s3, s11
	s_add_u32 s44, s44, 0x100
	s_addc_u32 s11, s11, 0
	s_add_u32 s46, s20, s0
	s_addc_u32 s47, s21, s1
	s_add_i32 s10, s10, 3
	s_cmp_ge_u32 s10, s84
	s_cselect_b32 s45, s86, 0
	s_cselect_b32 s10, s85, 0
	s_add_u32 s45, s45, s0
	s_addc_u32 s10, s10, s1
	s_add_u32 s45, s2, s45
	s_addc_u32 s10, s3, s10
	s_add_u32 s78, s45, 0x180
	s_addc_u32 s10, s10, 0
	s_cmp_eq_u32 s22, s0
	s_cselect_b32 s45, s41, s11
	s_cselect_b32 s44, s40, s44
	s_cselect_b32 s47, s43, s47
	s_cselect_b32 s46, s42, s46
	s_cselect_b32 s11, s19, s10
	s_cselect_b32 s10, s18, s78
	s_add_i32 s81, 0, 0x10000
	v_add_u32_e32 v0, s81, v205
	s_add_i32 s82, 0, 0x14000
	ds_read_b128 v[134:137], v0
	ds_read_b128 v[138:141], v0 offset:1024
	ds_read_b128 v[142:145], v0 offset:2048
	ds_read_b128 v[146:149], v0 offset:3072
	v_add_u32_e32 v0, s82, v205
	ds_read_b128 v[150:153], v0
	ds_read_b128 v[154:157], v0 offset:1024
	ds_read_b128 v[158:161], v0 offset:2048
	ds_read_b128 v[162:165], v0 offset:3072
	s_add_u32 s78, s27, s0
	s_addc_u32 s79, s79, s1
	v_lshl_add_u64 v[214:215], v[130:131], 0, s[78:79]
	s_add_i32 m0, s58, 0xc000
	ds_read_b128 v[166:169], v246
	ds_read_b128 v[170:173], v246 offset:1024
	ds_read_b128 v[174:177], v246 offset:2048
	ds_read_b128 v[178:181], v246 offset:3072
	ds_read_b128 v[182:185], v246 offset:4096
	ds_read_b128 v[186:189], v246 offset:5120
	ds_read_b128 v[190:193], v246 offset:6144
	ds_read_b128 v[210:213], v246 offset:7168
	global_load_lds_dwordx4 v[214:215], off
	v_lshl_add_u64 v[214:215], v[132:133], 0, s[78:79]
	s_add_i32 m0, s58, 0xe000
	s_nop 0
	global_load_lds_dwordx4 v[214:215], off
	s_waitcnt vmcnt(8)
	s_waitcnt lgkmcnt(0)
	s_barrier
	s_setprio 1
	s_waitcnt lgkmcnt(0)
	v_mfma_f32_16x16x32_bf16 v[122:125], v[134:137], v[166:169], 0
	v_mfma_f32_16x16x32_bf16 v[114:117], v[142:145], v[166:169], 0
	v_mfma_f32_16x16x32_bf16 v[106:109], v[134:137], v[174:177], 0
	v_mfma_f32_16x16x32_bf16 v[98:101], v[142:145], v[174:177], 0
	v_mfma_f32_16x16x32_bf16 v[90:93], v[134:137], v[182:185], 0
	v_mfma_f32_16x16x32_bf16 v[82:85], v[142:145], v[182:185], 0
	v_mfma_f32_16x16x32_bf16 v[74:77], v[134:137], v[190:193], 0
	v_mfma_f32_16x16x32_bf16 v[66:69], v[142:145], v[190:193], 0
	v_mfma_f32_16x16x32_bf16 v[122:125], v[138:141], v[170:173], v[122:125]
	v_mfma_f32_16x16x32_bf16 v[114:117], v[146:149], v[170:173], v[114:117]
	v_mfma_f32_16x16x32_bf16 v[106:109], v[138:141], v[178:181], v[106:109]
	v_mfma_f32_16x16x32_bf16 v[98:101], v[146:149], v[178:181], v[98:101]
	v_mfma_f32_16x16x32_bf16 v[90:93], v[138:141], v[186:189], v[90:93]
	v_mfma_f32_16x16x32_bf16 v[82:85], v[146:149], v[186:189], v[82:85]
	v_mfma_f32_16x16x32_bf16 v[74:77], v[138:141], v[210:213], v[74:77]
	v_mfma_f32_16x16x32_bf16 v[66:69], v[146:149], v[210:213], v[66:69]
	v_mfma_f32_16x16x32_bf16 v[126:129], v[150:153], v[166:169], 0
	v_mfma_f32_16x16x32_bf16 v[118:121], v[158:161], v[166:169], 0
	v_mfma_f32_16x16x32_bf16 v[110:113], v[150:153], v[174:177], 0
	v_mfma_f32_16x16x32_bf16 v[102:105], v[158:161], v[174:177], 0
	v_mfma_f32_16x16x32_bf16 v[94:97], v[150:153], v[182:185], 0
	v_mfma_f32_16x16x32_bf16 v[86:89], v[158:161], v[182:185], 0
	v_mfma_f32_16x16x32_bf16 v[78:81], v[150:153], v[190:193], 0
	v_mfma_f32_16x16x32_bf16 v[70:73], v[158:161], v[190:193], 0
	v_mfma_f32_16x16x32_bf16 v[126:129], v[154:157], v[170:173], v[126:129]
	v_mfma_f32_16x16x32_bf16 v[118:121], v[162:165], v[170:173], v[118:121]
	v_mfma_f32_16x16x32_bf16 v[110:113], v[154:157], v[178:181], v[110:113]
	v_mfma_f32_16x16x32_bf16 v[102:105], v[162:165], v[178:181], v[102:105]
	v_mfma_f32_16x16x32_bf16 v[94:97], v[154:157], v[186:189], v[94:97]
	v_mfma_f32_16x16x32_bf16 v[86:89], v[162:165], v[186:189], v[86:89]
	v_mfma_f32_16x16x32_bf16 v[78:81], v[154:157], v[210:213], v[78:81]
	v_mfma_f32_16x16x32_bf16 v[70:73], v[162:165], v[210:213], v[70:73]
	s_setprio 0
	s_barrier
	s_add_i32 s27, s81, s55
	v_lshl_add_u64 v[214:215], s[46:47], 0, v[202:203]
	s_mov_b32 m0, s27
	ds_read_b128 v[166:169], v246 offset:16384
	ds_read_b128 v[170:173], v246 offset:17408
	ds_read_b128 v[174:177], v246 offset:18432
	ds_read_b128 v[178:181], v246 offset:19456
	ds_read_b128 v[182:185], v246 offset:20480
	ds_read_b128 v[186:189], v246 offset:21504
	ds_read_b128 v[190:193], v246 offset:22528
	ds_read_b128 v[210:213], v246 offset:23552
	global_load_lds_dwordx4 v[214:215], off
	s_add_i32 m0, s27, 0x2000
	v_lshl_add_u64 v[216:217], s[46:47], 0, v[198:199]
	s_add_u32 s46, s46, s52
	s_addc_u32 s47, s47, 0
	s_add_i32 s27, s82, s55
	global_load_lds_dwordx4 v[216:217], off
	v_lshl_add_u64 v[218:219], s[46:47], 0, v[202:203]
	s_mov_b32 m0, s27
	v_lshl_add_u64 v[220:221], s[46:47], 0, v[198:199]
	global_load_lds_dwordx4 v[218:219], off
	s_add_i32 m0, s27, 0x2000
	v_lshl_add_u64 v[234:235], s[44:45], 0, v[200:201]
	global_load_lds_dwordx4 v[220:221], off
	s_mov_b32 m0, s58
	s_nop 0
	global_load_lds_dwordx4 v[234:235], off
	v_lshl_add_u64 v[234:235], s[44:45], 0, v[196:197]
	s_mov_b32 m0, s59
	s_nop 0
	global_load_lds_dwordx4 v[234:235], off
	s_waitcnt vmcnt(8)
	s_waitcnt lgkmcnt(0)
	s_barrier
; #define PG8_STAGE(bufoff, gbase, voff) do { _Pragma("unroll") for (int _i = 0; _i < 2; ++_i) \
;         __builtin_amdgcn_global_load_lds((const unsigned*)((const char*)(gbase) + (voff)[_i]), (PG8_LAS unsigned*)(lds + (bufoff) + ldsw + _i * 8192), 16, 0, 0); } while (0)
; #define PG8_LDA(dst, b, h) do { _Pragma("unroll") for (int m = 0; m < 4; ++m) _Pragma("unroll") for (int k = 0; k < 2; ++k) dst[m][k] = *(const PG8_LAS bf16x8*)(lds + PG8_SA(b, h) + aoff + m * 2048 + k * 1024); } while (0)
; #define PG8_LDB(dst, b, h) do { _Pragma("unroll") for (int n = 0; n < 2; ++n) _Pragma("unroll") for (int k = 0; k < 2; ++k) dst[n][k] = *(const PG8_LAS bf16x8*)(lds + PG8_SB(b, h) + boff + n * 2048 + k * 1024); } while (0)
; #define PG8_MMA(ai, bj, At, Bt) do { __builtin_amdgcn_s_setprio(1); _Pragma("unroll") for (int m = 0; m < 4; ++m) _Pragma("unroll") for (int n = 0; n < 2; ++n) _Pragma("unroll") for (int k = 0; k < 2; ++k) \
;         acc[ai][bj][m][n] = __builtin_amdgcn_mfma_f32_16x16x32_bf16(Bt[n][k], At[m][k], acc[ai][bj][m][n], 0, 0, 0); __builtin_amdgcn_s_setprio(0); } while (0)
; #define PG8_WAIT_V(n) asm volatile("s_waitcnt vmcnt(" #n ")" ::: "memory")
; #define PG8_WAIT_L(n) asm volatile("s_waitcnt lgkmcnt(" #n ")" ::: "memory")
; #define PG8_BAR __builtin_amdgcn_s_barrier()
; #define PG8_SCHED __builtin_amdgcn_sched_barrier(0)
; template <class Epi, class Sched, bool ALIGN_EPI = false, bool SP2 = false>
; __device__ __forceinline__ void gemm_phase(PG8_LAS unsigned char* lds, const Gemm g, const Sched& S, const Epi& E, int tid_in) {
;     ...
;             PG8_WAIT_V(8); PG8_WAIT_L(0); PG8_BAR; PG8_MMA(0, 0, At, B0); PG8_MMA(0, 1, At, B1); PG8_BAR; PG8_SCHED;
;             PG8_LDA(At, 0, 1); PG8_STAGE(PG8_SB(0, 0), b2, voffB); PG8_STAGE(PG8_SB(0, 1), b2 + hstep, voffB); PG8_STAGE(PG8_SA(0, 0), a2, voffA);
;             PG8_WAIT_V(8); PG8_WAIT_L(0); PG8_BAR; PG8_MMA(1, 0, At, B0); PG8_MMA(1, 1, At, B1); PG8_BAR; PG8_SCHED;
;             PG8_LDB(B0, 1, 0); PG8_LDB(B1, 1, 1); PG8_SCHED; PG8_LDA(At, 1, 0); PG8_STAGE(PG8_SA(0, 1), a2 + hstepA, voffA);
;             PG8_WAIT_V(8); PG8_WAIT_L(0); PG8_BAR; PG8_MMA(0, 0, At, B0); PG8_MMA(0, 1, At, B1); PG8_BAR; PG8_SCHED;
	s_setprio 1
	s_waitcnt lgkmcnt(0)
	v_mfma_f32_16x16x32_bf16 v[58:61], v[134:137], v[166:169], 0
	v_mfma_f32_16x16x32_bf16 v[50:53], v[142:145], v[166:169], 0
	v_mfma_f32_16x16x32_bf16 v[42:45], v[134:137], v[174:177], 0
	v_mfma_f32_16x16x32_bf16 v[34:37], v[142:145], v[174:177], 0
	v_mfma_f32_16x16x32_bf16 v[26:29], v[134:137], v[182:185], 0
	v_mfma_f32_16x16x32_bf16 v[18:21], v[142:145], v[182:185], 0
	v_mfma_f32_16x16x32_bf16 v[10:13], v[134:137], v[190:193], 0
	v_mfma_f32_16x16x32_bf16 v[6:9], v[142:145], v[190:193], 0
	v_mfma_f32_16x16x32_bf16 v[58:61], v[138:141], v[170:173], v[58:61]
	v_mfma_f32_16x16x32_bf16 v[50:53], v[146:149], v[170:173], v[50:53]
	v_mfma_f32_16x16x32_bf16 v[42:45], v[138:141], v[178:181], v[42:45]
	v_mfma_f32_16x16x32_bf16 v[34:37], v[146:149], v[178:181], v[34:37]
	v_mfma_f32_16x16x32_bf16 v[26:29], v[138:141], v[186:189], v[26:29]
	v_mfma_f32_16x16x32_bf16 v[18:21], v[146:149], v[186:189], v[18:21]
	v_mfma_f32_16x16x32_bf16 v[10:13], v[138:141], v[210:213], v[10:13]
	v_mfma_f32_16x16x32_bf16 v[6:9], v[146:149], v[210:213], v[6:9]
	v_mfma_f32_16x16x32_bf16 v[62:65], v[150:153], v[166:169], 0
	v_mfma_f32_16x16x32_bf16 v[54:57], v[158:161], v[166:169], 0
	v_mfma_f32_16x16x32_bf16 v[46:49], v[150:153], v[174:177], 0
	v_mfma_f32_16x16x32_bf16 v[38:41], v[158:161], v[174:177], 0
	v_mfma_f32_16x16x32_bf16 v[30:33], v[150:153], v[182:185], 0
	v_mfma_f32_16x16x32_bf16 v[22:25], v[158:161], v[182:185], 0
	v_mfma_f32_16x16x32_bf16 v[14:17], v[150:153], v[190:193], 0
	v_mfma_f32_16x16x32_bf16 v[2:5], v[158:161], v[190:193], 0
	v_mfma_f32_16x16x32_bf16 v[62:65], v[154:157], v[170:173], v[62:65]
	v_mfma_f32_16x16x32_bf16 v[54:57], v[162:165], v[170:173], v[54:57]
	v_mfma_f32_16x16x32_bf16 v[46:49], v[154:157], v[178:181], v[46:49]
	v_mfma_f32_16x16x32_bf16 v[38:41], v[162:165], v[178:181], v[38:41]
	v_mfma_f32_16x16x32_bf16 v[30:33], v[154:157], v[186:189], v[30:33]
	v_mfma_f32_16x16x32_bf16 v[22:25], v[162:165], v[186:189], v[22:25]
	v_mfma_f32_16x16x32_bf16 v[14:17], v[154:157], v[210:213], v[14:17]
	v_mfma_f32_16x16x32_bf16 v[2:5], v[162:165], v[210:213], v[2:5]
	s_setprio 0
	s_barrier
	s_add_i32 s27, 0, 0x18000
	v_add_u32_e32 v0, s27, v205
	s_add_i32 s46, 0, 0x1c000
	ds_read_b128 v[134:137], v0
	ds_read_b128 v[138:141], v0 offset:1024
	ds_read_b128 v[142:145], v0 offset:2048
	ds_read_b128 v[146:149], v0 offset:3072
	v_add_u32_e32 v0, s46, v205
	ds_read_b128 v[150:153], v0
	ds_read_b128 v[154:157], v0 offset:1024
	ds_read_b128 v[158:161], v0 offset:2048
	ds_read_b128 v[162:165], v0 offset:3072
	s_add_u32 s44, s44, s28
	s_addc_u32 s45, s45, 0
	s_mov_b32 m0, s60
	v_lshl_add_u64 v[234:235], s[44:45], 0, v[200:201]
	ds_read_b128 v[166:169], v246 offset:32768
	ds_read_b128 v[170:173], v246 offset:33792
	ds_read_b128 v[174:177], v246 offset:34816
	ds_read_b128 v[178:181], v246 offset:35840
	ds_read_b128 v[182:185], v246 offset:36864
	ds_read_b128 v[186:189], v246 offset:37888
	ds_read_b128 v[190:193], v246 offset:38912
	ds_read_b128 v[210:213], v246 offset:39936
	global_load_lds_dwordx4 v[234:235], off
	v_lshl_add_u64 v[234:235], s[44:45], 0, v[196:197]
	s_mov_b32 m0, s61
	s_nop 0
	global_load_lds_dwordx4 v[234:235], off
	s_waitcnt vmcnt(8)
	s_waitcnt lgkmcnt(0)
	s_barrier
	s_setprio 1
	s_waitcnt lgkmcnt(0)
	v_mfma_f32_16x16x32_bf16 v[122:125], v[134:137], v[166:169], v[122:125]
	v_mfma_f32_16x16x32_bf16 v[114:117], v[142:145], v[166:169], v[114:117]
	v_mfma_f32_16x16x32_bf16 v[106:109], v[134:137], v[174:177], v[106:109]
	v_mfma_f32_16x16x32_bf16 v[98:101], v[142:145], v[174:177], v[98:101]
	v_mfma_f32_16x16x32_bf16 v[90:93], v[134:137], v[182:185], v[90:93]
	v_mfma_f32_16x16x32_bf16 v[82:85], v[142:145], v[182:185], v[82:85]
	v_mfma_f32_16x16x32_bf16 v[74:77], v[134:137], v[190:193], v[74:77]
	v_mfma_f32_16x16x32_bf16 v[66:69], v[142:145], v[190:193], v[66:69]
	v_mfma_f32_16x16x32_bf16 v[122:125], v[138:141], v[170:173], v[122:125]
	v_mfma_f32_16x16x32_bf16 v[114:117], v[146:149], v[170:173], v[114:117]
	v_mfma_f32_16x16x32_bf16 v[106:109], v[138:141], v[178:181], v[106:109]
	v_mfma_f32_16x16x32_bf16 v[98:101], v[146:149], v[178:181], v[98:101]
	v_mfma_f32_16x16x32_bf16 v[90:93], v[138:141], v[186:189], v[90:93]
	v_mfma_f32_16x16x32_bf16 v[82:85], v[146:149], v[186:189], v[82:85]
	v_mfma_f32_16x16x32_bf16 v[74:77], v[138:141], v[210:213], v[74:77]
	v_mfma_f32_16x16x32_bf16 v[66:69], v[146:149], v[210:213], v[66:69]
	v_mfma_f32_16x16x32_bf16 v[126:129], v[150:153], v[166:169], v[126:129]
	v_mfma_f32_16x16x32_bf16 v[118:121], v[158:161], v[166:169], v[118:121]
	v_mfma_f32_16x16x32_bf16 v[110:113], v[150:153], v[174:177], v[110:113]
	v_mfma_f32_16x16x32_bf16 v[102:105], v[158:161], v[174:177], v[102:105]
	v_mfma_f32_16x16x32_bf16 v[94:97], v[150:153], v[182:185], v[94:97]
	v_mfma_f32_16x16x32_bf16 v[86:89], v[158:161], v[182:185], v[86:89]
	v_mfma_f32_16x16x32_bf16 v[78:81], v[150:153], v[190:193], v[78:81]
	v_mfma_f32_16x16x32_bf16 v[70:73], v[158:161], v[190:193], v[70:73]
	v_mfma_f32_16x16x32_bf16 v[126:129], v[154:157], v[170:173], v[126:129]
	v_mfma_f32_16x16x32_bf16 v[118:121], v[162:165], v[170:173], v[118:121]
	v_mfma_f32_16x16x32_bf16 v[110:113], v[154:157], v[178:181], v[110:113]
	v_mfma_f32_16x16x32_bf16 v[102:105], v[162:165], v[178:181], v[102:105]
	v_mfma_f32_16x16x32_bf16 v[94:97], v[154:157], v[186:189], v[94:97]
	v_mfma_f32_16x16x32_bf16 v[86:89], v[162:165], v[186:189], v[86:89]
	v_mfma_f32_16x16x32_bf16 v[78:81], v[154:157], v[210:213], v[78:81]
	v_mfma_f32_16x16x32_bf16 v[70:73], v[162:165], v[210:213], v[70:73]
	s_setprio 0
	s_barrier
; #define PG8_STAGE(bufoff, gbase, voff) do { _Pragma("unroll") for (int _i = 0; _i < 2; ++_i) \
;         __builtin_amdgcn_global_load_lds((const unsigned*)((const char*)(gbase) + (voff)[_i]), (PG8_LAS unsigned*)(lds + (bufoff) + ldsw + _i * 8192), 16, 0, 0); } while (0)
; #define PG8_LDA(dst, b, h) do { _Pragma("unroll") for (int m = 0; m < 4; ++m) _Pragma("unroll") for (int k = 0; k < 2; ++k) dst[m][k] = *(const PG8_LAS bf16x8*)(lds + PG8_SA(b, h) + aoff + m * 2048 + k * 1024); } while (0)
; #define PG8_MMA(ai, bj, At, Bt) do { __builtin_amdgcn_s_setprio(1); _Pragma("unroll") for (int m = 0; m < 4; ++m) _Pragma("unroll") for (int n = 0; n < 2; ++n) _Pragma("unroll") for (int k = 0; k < 2; ++k) \
;         acc[ai][bj][m][n] = __builtin_amdgcn_mfma_f32_16x16x32_bf16(Bt[n][k], At[m][k], acc[ai][bj][m][n], 0, 0, 0); __builtin_amdgcn_s_setprio(0); } while (0)
; #define PG8_WAIT_V(n) asm volatile("s_waitcnt vmcnt(" #n ")" ::: "memory")
; #define PG8_WAIT_L(n) asm volatile("s_waitcnt lgkmcnt(" #n ")" ::: "memory")
; #define PG8_BAR __builtin_amdgcn_s_barrier()
; #define PG8_SCHED __builtin_amdgcn_sched_barrier(0)
; template <class Epi, class Sched, bool ALIGN_EPI = false, bool SP2 = false>
; __device__ __forceinline__ void gemm_phase(PG8_LAS unsigned char* lds, const Gemm g, const Sched& S, const Epi& E, int tid_in) {
;     ...
;         for (int t = 0; t < ntc; t += 2) {
;     ...
;             PG8_WAIT_V(8); PG8_WAIT_L(0); PG8_BAR; PG8_MMA(0, 0, At, B0); PG8_MMA(0, 1, At, B1); PG8_BAR; PG8_SCHED;
;             PG8_LDA(At, 1, 1); PG8_STAGE(PG8_SB(1, 0), b3, voffB); PG8_STAGE(PG8_SB(1, 1), b3 + hstep, voffB); PG8_STAGE(PG8_SA(1, 0), a3, voffA);
;             PG8_WAIT_V(8); PG8_WAIT_L(0); PG8_BAR; PG8_MMA(1, 0, At, B0); PG8_MMA(1, 1, At, B1); PG8_BAR; PG8_SCHED;
	s_add_i32 s27, s27, s55
	v_lshl_add_u64 v[214:215], v[214:215], 0, s[96:97]
	s_mov_b32 m0, s27
	ds_read_b128 v[166:169], v246 offset:49152
	ds_read_b128 v[170:173], v246 offset:50176
	ds_read_b128 v[174:177], v246 offset:51200
	ds_read_b128 v[178:181], v246 offset:52224
	ds_read_b128 v[182:185], v246 offset:53248
	ds_read_b128 v[186:189], v246 offset:54272
	ds_read_b128 v[190:193], v246 offset:55296
	ds_read_b128 v[210:213], v246 offset:56320
	global_load_lds_dwordx4 v[214:215], off
	v_lshl_add_u64 v[214:215], v[216:217], 0, s[96:97]
	s_add_i32 m0, s27, 0x2000
	s_add_i32 s27, s46, s55
	global_load_lds_dwordx4 v[214:215], off
	v_lshl_add_u64 v[214:215], v[218:219], 0, s[96:97]
	s_mov_b32 m0, s27
	s_nop 0
	global_load_lds_dwordx4 v[214:215], off
	v_lshl_add_u64 v[214:215], v[220:221], 0, s[96:97]
	s_add_i32 m0, s27, 0x2000
	s_nop 0
	global_load_lds_dwordx4 v[214:215], off
	v_lshl_add_u64 v[214:215], s[10:11], 0, v[200:201]
	s_mov_b32 m0, s63
	s_nop 0
	global_load_lds_dwordx4 v[214:215], off
	v_lshl_add_u64 v[214:215], s[10:11], 0, v[196:197]
	s_mov_b32 m0, s64
	s_nop 0
	global_load_lds_dwordx4 v[214:215], off
	s_waitcnt vmcnt(8)
	s_waitcnt lgkmcnt(0)
	s_barrier
	s_setprio 1
	s_waitcnt lgkmcnt(0)
	v_mfma_f32_16x16x32_bf16 v[58:61], v[134:137], v[166:169], v[58:61]
	v_mfma_f32_16x16x32_bf16 v[50:53], v[142:145], v[166:169], v[50:53]
	v_mfma_f32_16x16x32_bf16 v[42:45], v[134:137], v[174:177], v[42:45]
	v_mfma_f32_16x16x32_bf16 v[34:37], v[142:145], v[174:177], v[34:37]
	v_mfma_f32_16x16x32_bf16 v[26:29], v[134:137], v[182:185], v[26:29]
	v_mfma_f32_16x16x32_bf16 v[18:21], v[142:145], v[182:185], v[18:21]
	v_mfma_f32_16x16x32_bf16 v[10:13], v[134:137], v[190:193], v[10:13]
	v_mfma_f32_16x16x32_bf16 v[6:9], v[142:145], v[190:193], v[6:9]
	v_mfma_f32_16x16x32_bf16 v[58:61], v[138:141], v[170:173], v[58:61]
	v_mfma_f32_16x16x32_bf16 v[50:53], v[146:149], v[170:173], v[50:53]
	v_mfma_f32_16x16x32_bf16 v[42:45], v[138:141], v[178:181], v[42:45]
	v_mfma_f32_16x16x32_bf16 v[34:37], v[146:149], v[178:181], v[34:37]
	v_mfma_f32_16x16x32_bf16 v[26:29], v[138:141], v[186:189], v[26:29]
	v_mfma_f32_16x16x32_bf16 v[18:21], v[146:149], v[186:189], v[18:21]
	v_mfma_f32_16x16x32_bf16 v[10:13], v[138:141], v[210:213], v[10:13]
	v_mfma_f32_16x16x32_bf16 v[6:9], v[146:149], v[210:213], v[6:9]
	v_mfma_f32_16x16x32_bf16 v[62:65], v[150:153], v[166:169], v[62:65]
	v_mfma_f32_16x16x32_bf16 v[54:57], v[158:161], v[166:169], v[54:57]
	v_mfma_f32_16x16x32_bf16 v[46:49], v[150:153], v[174:177], v[46:49]
	v_mfma_f32_16x16x32_bf16 v[38:41], v[158:161], v[174:177], v[38:41]
	v_mfma_f32_16x16x32_bf16 v[30:33], v[150:153], v[182:185], v[30:33]
	v_mfma_f32_16x16x32_bf16 v[22:25], v[158:161], v[182:185], v[22:25]
	v_mfma_f32_16x16x32_bf16 v[14:17], v[150:153], v[190:193], v[14:17]
	v_mfma_f32_16x16x32_bf16 v[2:5], v[158:161], v[190:193], v[2:5]
	v_mfma_f32_16x16x32_bf16 v[62:65], v[154:157], v[170:173], v[62:65]
	v_mfma_f32_16x16x32_bf16 v[54:57], v[162:165], v[170:173], v[54:57]
	v_mfma_f32_16x16x32_bf16 v[46:49], v[154:157], v[178:181], v[46:49]
	v_mfma_f32_16x16x32_bf16 v[38:41], v[162:165], v[178:181], v[38:41]
	v_mfma_f32_16x16x32_bf16 v[30:33], v[154:157], v[186:189], v[30:33]
	v_mfma_f32_16x16x32_bf16 v[22:25], v[162:165], v[186:189], v[22:25]
	v_mfma_f32_16x16x32_bf16 v[14:17], v[154:157], v[210:213], v[14:17]
	v_mfma_f32_16x16x32_bf16 v[2:5], v[162:165], v[210:213], v[2:5]
	s_setprio 0
	s_barrier
	s_add_u32 s0, s0, 0x100
	s_addc_u32 s1, s1, 0
	s_cmp_ge_u32 s23, s94
	s_mov_b32 s10, s23
	s_cbranch_scc1 .Lzk0_exit
.LBB0_606:
	s_or_b32 s11, s10, 1
	s_cmp_ge_u32 s11, s84
	s_cselect_b32 s27, s86, 0
	s_cselect_b32 s79, s85, 0
	s_add_i32 s23, s10, 2
	s_cmp_ge_u32 s23, s84
	s_cselect_b32 s44, s86, 0
	s_cselect_b32 s11, s85, 0
	s_add_u32 s44, s44, s0
	s_addc_u32 s11, s11, s1
	s_add_u32 s44, s2, s44
	s_addc_u32 s11, s3, s11
	s_add_u32 s44, s44, 0x100
	s_addc_u32 s11, s11, 0
	s_add_u32 s46, s20, s0
	s_addc_u32 s47, s21, s1
	s_add_i32 s10, s10, 3
	s_cmp_ge_u32 s10, s84
	s_cselect_b32 s45, s86, 0
	s_cselect_b32 s10, s85, 0
	s_add_u32 s45, s45, s0
	s_addc_u32 s10, s10, s1
	s_add_u32 s45, s2, s45
	s_addc_u32 s10, s3, s10
	s_add_u32 s78, s45, 0x180
	s_addc_u32 s10, s10, 0
	s_cmp_eq_u32 s22, s0
	s_cselect_b32 s45, s41, s11
	s_cselect_b32 s44, s40, s44
	s_cselect_b32 s47, s43, s47
	s_cselect_b32 s46, s42, s46
	s_cselect_b32 s11, s19, s10
	s_cselect_b32 s10, s18, s78
	s_add_i32 s81, 0, 0x10000
	v_add_u32_e32 v0, s81, v205
	s_add_i32 s82, 0, 0x14000
	ds_read_b128 v[134:137], v0
	ds_read_b128 v[138:141], v0 offset:1024
	ds_read_b128 v[142:145], v0 offset:2048
	ds_read_b128 v[146:149], v0 offset:3072
	v_add_u32_e32 v0, s82, v205
	ds_read_b128 v[150:153], v0
	ds_read_b128 v[154:157], v0 offset:1024
	ds_read_b128 v[158:161], v0 offset:2048
	ds_read_b128 v[162:165], v0 offset:3072
	s_add_u32 s78, s27, s0
	s_addc_u32 s79, s79, s1
	v_lshl_add_u64 v[214:215], v[130:131], 0, s[78:79]
	s_add_i32 m0, s58, 0xc000
	ds_read_b128 v[166:169], v246
	ds_read_b128 v[170:173], v246 offset:1024
	ds_read_b128 v[174:177], v246 offset:2048
	ds_read_b128 v[178:181], v246 offset:3072
	ds_read_b128 v[182:185], v246 offset:4096
	ds_read_b128 v[186:189], v246 offset:5120
	ds_read_b128 v[190:193], v246 offset:6144
	ds_read_b128 v[210:213], v246 offset:7168
	global_load_lds_dwordx4 v[214:215], off
	v_lshl_add_u64 v[214:215], v[132:133], 0, s[78:79]
	s_add_i32 m0, s58, 0xe000
	s_nop 0
	global_load_lds_dwordx4 v[214:215], off
	s_waitcnt vmcnt(8)
	s_waitcnt lgkmcnt(0)
	s_barrier
; #define PG8_STAGE(bufoff, gbase, voff) do { _Pragma("unroll") for (int _i = 0; _i < 2; ++_i) \
;         __builtin_amdgcn_global_load_lds((const unsigned*)((const char*)(gbase) + (voff)[_i]), (PG8_LAS unsigned*)(lds + (bufoff) + ldsw + _i * 8192), 16, 0, 0); } while (0)
; #define PG8_LDA(dst, b, h) do { _Pragma("unroll") for (int m = 0; m < 4; ++m) _Pragma("unroll") for (int k = 0; k < 2; ++k) dst[m][k] = *(const PG8_LAS bf16x8*)(lds + PG8_SA(b, h) + aoff + m * 2048 + k * 1024); } while (0)
; #define PG8_LDB(dst, b, h) do { _Pragma("unroll") for (int n = 0; n < 2; ++n) _Pragma("unroll") for (int k = 0; k < 2; ++k) dst[n][k] = *(const PG8_LAS bf16x8*)(lds + PG8_SB(b, h) + boff + n * 2048 + k * 1024); } while (0)
; #define PG8_MMA(ai, bj, At, Bt) do { __builtin_amdgcn_s_setprio(1); _Pragma("unroll") for (int m = 0; m < 4; ++m) _Pragma("unroll") for (int n = 0; n < 2; ++n) _Pragma("unroll") for (int k = 0; k < 2; ++k) \
;         acc[ai][bj][m][n] = __builtin_amdgcn_mfma_f32_16x16x32_bf16(Bt[n][k], At[m][k], acc[ai][bj][m][n], 0, 0, 0); __builtin_amdgcn_s_setprio(0); } while (0)
; #define PG8_WAIT_V(n) asm volatile("s_waitcnt vmcnt(" #n ")" ::: "memory")
; #define PG8_WAIT_L(n) asm volatile("s_waitcnt lgkmcnt(" #n ")" ::: "memory")
; #define PG8_BAR __builtin_amdgcn_s_barrier()
; #define PG8_SCHED __builtin_amdgcn_sched_barrier(0)
; template <class Epi, class Sched, bool ALIGN_EPI = false, bool SP2 = false>
; __device__ __forceinline__ void gemm_phase(PG8_LAS unsigned char* lds, const Gemm g, const Sched& S, const Epi& E, int tid_in) {
;     ...
;             PG8_LDB(B0, 0, 0); PG8_LDB(B1, 0, 1); PG8_SCHED; PG8_LDA(At, 0, 0); PG8_STAGE(PG8_SA(1, 1), a1 + hstepA, voffA);
;             PG8_WAIT_V(8); PG8_WAIT_L(0); PG8_BAR; PG8_MMA(0, 0, At, B0); PG8_MMA(0, 1, At, B1); PG8_BAR; PG8_SCHED;
;             PG8_LDA(At, 0, 1); PG8_STAGE(PG8_SB(0, 0), b2, voffB); PG8_STAGE(PG8_SB(0, 1), b2 + hstep, voffB); PG8_STAGE(PG8_SA(0, 0), a2, voffA);
;             PG8_WAIT_V(8); PG8_WAIT_L(0); PG8_BAR; PG8_MMA(1, 0, At, B0); PG8_MMA(1, 1, At, B1); PG8_BAR; PG8_SCHED;
;             PG8_LDB(B0, 1, 0); PG8_LDB(B1, 1, 1); PG8_SCHED; PG8_LDA(At, 1, 0); PG8_STAGE(PG8_SA(0, 1), a2 + hstepA, voffA);
;             PG8_WAIT_V(8); PG8_WAIT_L(0); PG8_BAR; PG8_MMA(0, 0, At, B0); PG8_MMA(0, 1, At, B1); PG8_BAR; PG8_SCHED;
	s_setprio 1
	s_waitcnt lgkmcnt(0)
	v_mfma_f32_16x16x32_bf16 v[122:125], v[134:137], v[166:169], v[122:125]
	v_mfma_f32_16x16x32_bf16 v[114:117], v[142:145], v[166:169], v[114:117]
	v_mfma_f32_16x16x32_bf16 v[106:109], v[134:137], v[174:177], v[106:109]
	v_mfma_f32_16x16x32_bf16 v[98:101], v[142:145], v[174:177], v[98:101]
	v_mfma_f32_16x16x32_bf16 v[90:93], v[134:137], v[182:185], v[90:93]
	v_mfma_f32_16x16x32_bf16 v[82:85], v[142:145], v[182:185], v[82:85]
	v_mfma_f32_16x16x32_bf16 v[74:77], v[134:137], v[190:193], v[74:77]
	v_mfma_f32_16x16x32_bf16 v[66:69], v[142:145], v[190:193], v[66:69]
	v_mfma_f32_16x16x32_bf16 v[122:125], v[138:141], v[170:173], v[122:125]
	v_mfma_f32_16x16x32_bf16 v[114:117], v[146:149], v[170:173], v[114:117]
	v_mfma_f32_16x16x32_bf16 v[106:109], v[138:141], v[178:181], v[106:109]
	v_mfma_f32_16x16x32_bf16 v[98:101], v[146:149], v[178:181], v[98:101]
	v_mfma_f32_16x16x32_bf16 v[90:93], v[138:141], v[186:189], v[90:93]
	v_mfma_f32_16x16x32_bf16 v[82:85], v[146:149], v[186:189], v[82:85]
	v_mfma_f32_16x16x32_bf16 v[74:77], v[138:141], v[210:213], v[74:77]
	v_mfma_f32_16x16x32_bf16 v[66:69], v[146:149], v[210:213], v[66:69]
	v_mfma_f32_16x16x32_bf16 v[126:129], v[150:153], v[166:169], v[126:129]
	v_mfma_f32_16x16x32_bf16 v[118:121], v[158:161], v[166:169], v[118:121]
	v_mfma_f32_16x16x32_bf16 v[110:113], v[150:153], v[174:177], v[110:113]
	v_mfma_f32_16x16x32_bf16 v[102:105], v[158:161], v[174:177], v[102:105]
	v_mfma_f32_16x16x32_bf16 v[94:97], v[150:153], v[182:185], v[94:97]
	v_mfma_f32_16x16x32_bf16 v[86:89], v[158:161], v[182:185], v[86:89]
	v_mfma_f32_16x16x32_bf16 v[78:81], v[150:153], v[190:193], v[78:81]
	v_mfma_f32_16x16x32_bf16 v[70:73], v[158:161], v[190:193], v[70:73]
	v_mfma_f32_16x16x32_bf16 v[126:129], v[154:157], v[170:173], v[126:129]
	v_mfma_f32_16x16x32_bf16 v[118:121], v[162:165], v[170:173], v[118:121]
	v_mfma_f32_16x16x32_bf16 v[110:113], v[154:157], v[178:181], v[110:113]
	v_mfma_f32_16x16x32_bf16 v[102:105], v[162:165], v[178:181], v[102:105]
	v_mfma_f32_16x16x32_bf16 v[94:97], v[154:157], v[186:189], v[94:97]
	v_mfma_f32_16x16x32_bf16 v[86:89], v[162:165], v[186:189], v[86:89]
	v_mfma_f32_16x16x32_bf16 v[78:81], v[154:157], v[210:213], v[78:81]
	v_mfma_f32_16x16x32_bf16 v[70:73], v[162:165], v[210:213], v[70:73]
	s_setprio 0
	s_barrier
	s_add_i32 s27, s81, s55
	v_lshl_add_u64 v[214:215], s[46:47], 0, v[202:203]
	s_mov_b32 m0, s27
	ds_read_b128 v[166:169], v246 offset:16384
	ds_read_b128 v[170:173], v246 offset:17408
	ds_read_b128 v[174:177], v246 offset:18432
	ds_read_b128 v[178:181], v246 offset:19456
	ds_read_b128 v[182:185], v246 offset:20480
	ds_read_b128 v[186:189], v246 offset:21504
	ds_read_b128 v[190:193], v246 offset:22528
	ds_read_b128 v[210:213], v246 offset:23552
	global_load_lds_dwordx4 v[214:215], off
	s_add_i32 m0, s27, 0x2000
	v_lshl_add_u64 v[216:217], s[46:47], 0, v[198:199]
	s_add_u32 s46, s46, s52
	s_addc_u32 s47, s47, 0
	s_add_i32 s27, s82, s55
	global_load_lds_dwordx4 v[216:217], off
	v_lshl_add_u64 v[218:219], s[46:47], 0, v[202:203]
	s_mov_b32 m0, s27
	v_lshl_add_u64 v[220:221], s[46:47], 0, v[198:199]
	global_load_lds_dwordx4 v[218:219], off
	s_add_i32 m0, s27, 0x2000
	v_lshl_add_u64 v[234:235], s[44:45], 0, v[200:201]
	global_load_lds_dwordx4 v[220:221], off
	s_mov_b32 m0, s58
	s_nop 0
	global_load_lds_dwordx4 v[234:235], off
	v_lshl_add_u64 v[234:235], s[44:45], 0, v[196:197]
	s_mov_b32 m0, s59
	s_nop 0
	global_load_lds_dwordx4 v[234:235], off
	s_waitcnt vmcnt(8)
	s_waitcnt lgkmcnt(0)
	s_barrier
	s_setprio 1
	s_waitcnt lgkmcnt(0)
	v_mfma_f32_16x16x32_bf16 v[58:61], v[134:137], v[166:169], v[58:61]
	v_mfma_f32_16x16x32_bf16 v[50:53], v[142:145], v[166:169], v[50:53]
	v_mfma_f32_16x16x32_bf16 v[42:45], v[134:137], v[174:177], v[42:45]
	v_mfma_f32_16x16x32_bf16 v[34:37], v[142:145], v[174:177], v[34:37]
	v_mfma_f32_16x16x32_bf16 v[26:29], v[134:137], v[182:185], v[26:29]
	v_mfma_f32_16x16x32_bf16 v[18:21], v[142:145], v[182:185], v[18:21]
	v_mfma_f32_16x16x32_bf16 v[10:13], v[134:137], v[190:193], v[10:13]
	v_mfma_f32_16x16x32_bf16 v[6:9], v[142:145], v[190:193], v[6:9]
	v_mfma_f32_16x16x32_bf16 v[58:61], v[138:141], v[170:173], v[58:61]
	v_mfma_f32_16x16x32_bf16 v[50:53], v[146:149], v[170:173], v[50:53]
	v_mfma_f32_16x16x32_bf16 v[42:45], v[138:141], v[178:181], v[42:45]
	v_mfma_f32_16x16x32_bf16 v[34:37], v[146:149], v[178:181], v[34:37]
	v_mfma_f32_16x16x32_bf16 v[26:29], v[138:141], v[186:189], v[26:29]
	v_mfma_f32_16x16x32_bf16 v[18:21], v[146:149], v[186:189], v[18:21]
	v_mfma_f32_16x16x32_bf16 v[10:13], v[138:141], v[210:213], v[10:13]
	v_mfma_f32_16x16x32_bf16 v[6:9], v[146:149], v[210:213], v[6:9]
	v_mfma_f32_16x16x32_bf16 v[62:65], v[150:153], v[166:169], v[62:65]
	v_mfma_f32_16x16x32_bf16 v[54:57], v[158:161], v[166:169], v[54:57]
	v_mfma_f32_16x16x32_bf16 v[46:49], v[150:153], v[174:177], v[46:49]
	v_mfma_f32_16x16x32_bf16 v[38:41], v[158:161], v[174:177], v[38:41]
	v_mfma_f32_16x16x32_bf16 v[30:33], v[150:153], v[182:185], v[30:33]
	v_mfma_f32_16x16x32_bf16 v[22:25], v[158:161], v[182:185], v[22:25]
	v_mfma_f32_16x16x32_bf16 v[14:17], v[150:153], v[190:193], v[14:17]
	v_mfma_f32_16x16x32_bf16 v[2:5], v[158:161], v[190:193], v[2:5]
	v_mfma_f32_16x16x32_bf16 v[62:65], v[154:157], v[170:173], v[62:65]
	v_mfma_f32_16x16x32_bf16 v[54:57], v[162:165], v[170:173], v[54:57]
	v_mfma_f32_16x16x32_bf16 v[46:49], v[154:157], v[178:181], v[46:49]
	v_mfma_f32_16x16x32_bf16 v[38:41], v[162:165], v[178:181], v[38:41]
	v_mfma_f32_16x16x32_bf16 v[30:33], v[154:157], v[186:189], v[30:33]
	v_mfma_f32_16x16x32_bf16 v[22:25], v[162:165], v[186:189], v[22:25]
	v_mfma_f32_16x16x32_bf16 v[14:17], v[154:157], v[210:213], v[14:17]
	v_mfma_f32_16x16x32_bf16 v[2:5], v[162:165], v[210:213], v[2:5]
	s_setprio 0
	s_barrier
; #define PG8_STAGE(bufoff, gbase, voff) do { _Pragma("unroll") for (int _i = 0; _i < 2; ++_i) \
;         __builtin_amdgcn_global_load_lds((const unsigned*)((const char*)(gbase) + (voff)[_i]), (PG8_LAS unsigned*)(lds + (bufoff) + ldsw + _i * 8192), 16, 0, 0); } while (0)
; #define PG8_LDA(dst, b, h) do { _Pragma("unroll") for (int m = 0; m < 4; ++m) _Pragma("unroll") for (int k = 0; k < 2; ++k) dst[m][k] = *(const PG8_LAS bf16x8*)(lds + PG8_SA(b, h) + aoff + m * 2048 + k * 1024); } while (0)
; #define PG8_LDB(dst, b, h) do { _Pragma("unroll") for (int n = 0; n < 2; ++n) _Pragma("unroll") for (int k = 0; k < 2; ++k) dst[n][k] = *(const PG8_LAS bf16x8*)(lds + PG8_SB(b, h) + boff + n * 2048 + k * 1024); } while (0)
; #define PG8_MMA(ai, bj, At, Bt) do { __builtin_amdgcn_s_setprio(1); _Pragma("unroll") for (int m = 0; m < 4; ++m) _Pragma("unroll") for (int n = 0; n < 2; ++n) _Pragma("unroll") for (int k = 0; k < 2; ++k) \
;         acc[ai][bj][m][n] = __builtin_amdgcn_mfma_f32_16x16x32_bf16(Bt[n][k], At[m][k], acc[ai][bj][m][n], 0, 0, 0); __builtin_amdgcn_s_setprio(0); } while (0)
; #define PG8_WAIT_V(n) asm volatile("s_waitcnt vmcnt(" #n ")" ::: "memory")
; #define PG8_WAIT_L(n) asm volatile("s_waitcnt lgkmcnt(" #n ")" ::: "memory")
; #define PG8_BAR __builtin_amdgcn_s_barrier()
; #define PG8_SCHED __builtin_amdgcn_sched_barrier(0)
; template <class Epi, class Sched, bool ALIGN_EPI = false, bool SP2 = false>
; __device__ __forceinline__ void gemm_phase(PG8_LAS unsigned char* lds, const Gemm g, const Sched& S, const Epi& E, int tid_in) {
;     ...
;         for (int t = 0; t < ntc; t += 2) {
;     ...
;             PG8_LDB(B0, 1, 0); PG8_LDB(B1, 1, 1); PG8_SCHED; PG8_LDA(At, 1, 0); PG8_STAGE(PG8_SA(0, 1), a2 + hstepA, voffA);
;             PG8_WAIT_V(8); PG8_WAIT_L(0); PG8_BAR; PG8_MMA(0, 0, At, B0); PG8_MMA(0, 1, At, B1); PG8_BAR; PG8_SCHED;
;             PG8_LDA(At, 1, 1); PG8_STAGE(PG8_SB(1, 0), b3, voffB); PG8_STAGE(PG8_SB(1, 1), b3 + hstep, voffB); PG8_STAGE(PG8_SA(1, 0), a3, voffA);
;             PG8_WAIT_V(8); PG8_WAIT_L(0); PG8_BAR; PG8_MMA(1, 0, At, B0); PG8_MMA(1, 1, At, B1); PG8_BAR; PG8_SCHED;
	s_add_i32 s27, 0, 0x18000
	v_add_u32_e32 v0, s27, v205
	s_add_i32 s46, 0, 0x1c000
	ds_read_b128 v[134:137], v0
	ds_read_b128 v[138:141], v0 offset:1024
	ds_read_b128 v[142:145], v0 offset:2048
	ds_read_b128 v[146:149], v0 offset:3072
	v_add_u32_e32 v0, s46, v205
	ds_read_b128 v[150:153], v0
	ds_read_b128 v[154:157], v0 offset:1024
	ds_read_b128 v[158:161], v0 offset:2048
	ds_read_b128 v[162:165], v0 offset:3072
	s_add_u32 s44, s44, s28
	s_addc_u32 s45, s45, 0
	s_mov_b32 m0, s60
	v_lshl_add_u64 v[234:235], s[44:45], 0, v[200:201]
	ds_read_b128 v[166:169], v246 offset:32768
	ds_read_b128 v[170:173], v246 offset:33792
	ds_read_b128 v[174:177], v246 offset:34816
	ds_read_b128 v[178:181], v246 offset:35840
	ds_read_b128 v[182:185], v246 offset:36864
	ds_read_b128 v[186:189], v246 offset:37888
	ds_read_b128 v[190:193], v246 offset:38912
	ds_read_b128 v[210:213], v246 offset:39936
	global_load_lds_dwordx4 v[234:235], off
	v_lshl_add_u64 v[234:235], s[44:45], 0, v[196:197]
	s_mov_b32 m0, s61
	s_nop 0
	global_load_lds_dwordx4 v[234:235], off
	s_waitcnt vmcnt(8)
	s_waitcnt lgkmcnt(0)
	s_barrier
	s_setprio 1
	s_waitcnt lgkmcnt(0)
	v_mfma_f32_16x16x32_bf16 v[122:125], v[134:137], v[166:169], v[122:125]
	v_mfma_f32_16x16x32_bf16 v[114:117], v[142:145], v[166:169], v[114:117]
	v_mfma_f32_16x16x32_bf16 v[106:109], v[134:137], v[174:177], v[106:109]
	v_mfma_f32_16x16x32_bf16 v[98:101], v[142:145], v[174:177], v[98:101]
	v_mfma_f32_16x16x32_bf16 v[90:93], v[134:137], v[182:185], v[90:93]
	v_mfma_f32_16x16x32_bf16 v[82:85], v[142:145], v[182:185], v[82:85]
	v_mfma_f32_16x16x32_bf16 v[74:77], v[134:137], v[190:193], v[74:77]
	v_mfma_f32_16x16x32_bf16 v[66:69], v[142:145], v[190:193], v[66:69]
	v_mfma_f32_16x16x32_bf16 v[122:125], v[138:141], v[170:173], v[122:125]
	v_mfma_f32_16x16x32_bf16 v[114:117], v[146:149], v[170:173], v[114:117]
	v_mfma_f32_16x16x32_bf16 v[106:109], v[138:141], v[178:181], v[106:109]
	v_mfma_f32_16x16x32_bf16 v[98:101], v[146:149], v[178:181], v[98:101]
	v_mfma_f32_16x16x32_bf16 v[90:93], v[138:141], v[186:189], v[90:93]
	v_mfma_f32_16x16x32_bf16 v[82:85], v[146:149], v[186:189], v[82:85]
	v_mfma_f32_16x16x32_bf16 v[74:77], v[138:141], v[210:213], v[74:77]
	v_mfma_f32_16x16x32_bf16 v[66:69], v[146:149], v[210:213], v[66:69]
	v_mfma_f32_16x16x32_bf16 v[126:129], v[150:153], v[166:169], v[126:129]
	v_mfma_f32_16x16x32_bf16 v[118:121], v[158:161], v[166:169], v[118:121]
	v_mfma_f32_16x16x32_bf16 v[110:113], v[150:153], v[174:177], v[110:113]
	v_mfma_f32_16x16x32_bf16 v[102:105], v[158:161], v[174:177], v[102:105]
	v_mfma_f32_16x16x32_bf16 v[94:97], v[150:153], v[182:185], v[94:97]
	v_mfma_f32_16x16x32_bf16 v[86:89], v[158:161], v[182:185], v[86:89]
	v_mfma_f32_16x16x32_bf16 v[78:81], v[150:153], v[190:193], v[78:81]
	v_mfma_f32_16x16x32_bf16 v[70:73], v[158:161], v[190:193], v[70:73]
	v_mfma_f32_16x16x32_bf16 v[126:129], v[154:157], v[170:173], v[126:129]
	v_mfma_f32_16x16x32_bf16 v[118:121], v[162:165], v[170:173], v[118:121]
	v_mfma_f32_16x16x32_bf16 v[110:113], v[154:157], v[178:181], v[110:113]
	v_mfma_f32_16x16x32_bf16 v[102:105], v[162:165], v[178:181], v[102:105]
	v_mfma_f32_16x16x32_bf16 v[94:97], v[154:157], v[186:189], v[94:97]
	v_mfma_f32_16x16x32_bf16 v[86:89], v[162:165], v[186:189], v[86:89]
	v_mfma_f32_16x16x32_bf16 v[78:81], v[154:157], v[210:213], v[78:81]
	v_mfma_f32_16x16x32_bf16 v[70:73], v[162:165], v[210:213], v[70:73]
	s_setprio 0
	s_barrier
	s_add_i32 s27, s27, s55
	v_lshl_add_u64 v[214:215], v[214:215], 0, s[96:97]
	s_mov_b32 m0, s27
	ds_read_b128 v[166:169], v246 offset:49152
	ds_read_b128 v[170:173], v246 offset:50176
	ds_read_b128 v[174:177], v246 offset:51200
	ds_read_b128 v[178:181], v246 offset:52224
	ds_read_b128 v[182:185], v246 offset:53248
	ds_read_b128 v[186:189], v246 offset:54272
	ds_read_b128 v[190:193], v246 offset:55296
	ds_read_b128 v[210:213], v246 offset:56320
	global_load_lds_dwordx4 v[214:215], off
	v_lshl_add_u64 v[214:215], v[216:217], 0, s[96:97]
	s_add_i32 m0, s27, 0x2000
	s_add_i32 s27, s46, s55
	global_load_lds_dwordx4 v[214:215], off
	v_lshl_add_u64 v[214:215], v[218:219], 0, s[96:97]
	s_mov_b32 m0, s27
	s_nop 0
	global_load_lds_dwordx4 v[214:215], off
	v_lshl_add_u64 v[214:215], v[220:221], 0, s[96:97]
	s_add_i32 m0, s27, 0x2000
	s_nop 0
	global_load_lds_dwordx4 v[214:215], off
	v_lshl_add_u64 v[214:215], s[10:11], 0, v[200:201]
	s_mov_b32 m0, s63
	s_nop 0
	global_load_lds_dwordx4 v[214:215], off
	v_lshl_add_u64 v[214:215], s[10:11], 0, v[196:197]
	s_mov_b32 m0, s64
	s_nop 0
	global_load_lds_dwordx4 v[214:215], off
	s_waitcnt vmcnt(8)
	s_waitcnt lgkmcnt(0)
	s_barrier
	s_setprio 1
	s_waitcnt lgkmcnt(0)
	v_mfma_f32_16x16x32_bf16 v[58:61], v[134:137], v[166:169], v[58:61]
	v_mfma_f32_16x16x32_bf16 v[50:53], v[142:145], v[166:169], v[50:53]
	v_mfma_f32_16x16x32_bf16 v[42:45], v[134:137], v[174:177], v[42:45]
	v_mfma_f32_16x16x32_bf16 v[34:37], v[142:145], v[174:177], v[34:37]
	v_mfma_f32_16x16x32_bf16 v[26:29], v[134:137], v[182:185], v[26:29]
	v_mfma_f32_16x16x32_bf16 v[18:21], v[142:145], v[182:185], v[18:21]
	v_mfma_f32_16x16x32_bf16 v[10:13], v[134:137], v[190:193], v[10:13]
	v_mfma_f32_16x16x32_bf16 v[6:9], v[142:145], v[190:193], v[6:9]
	v_mfma_f32_16x16x32_bf16 v[58:61], v[138:141], v[170:173], v[58:61]
	v_mfma_f32_16x16x32_bf16 v[50:53], v[146:149], v[170:173], v[50:53]
	v_mfma_f32_16x16x32_bf16 v[42:45], v[138:141], v[178:181], v[42:45]
	v_mfma_f32_16x16x32_bf16 v[34:37], v[146:149], v[178:181], v[34:37]
	v_mfma_f32_16x16x32_bf16 v[26:29], v[138:141], v[186:189], v[26:29]
	v_mfma_f32_16x16x32_bf16 v[18:21], v[146:149], v[186:189], v[18:21]
	v_mfma_f32_16x16x32_bf16 v[10:13], v[138:141], v[210:213], v[10:13]
	v_mfma_f32_16x16x32_bf16 v[6:9], v[146:149], v[210:213], v[6:9]
	v_mfma_f32_16x16x32_bf16 v[62:65], v[150:153], v[166:169], v[62:65]
	v_mfma_f32_16x16x32_bf16 v[54:57], v[158:161], v[166:169], v[54:57]
	v_mfma_f32_16x16x32_bf16 v[46:49], v[150:153], v[174:177], v[46:49]
	v_mfma_f32_16x16x32_bf16 v[38:41], v[158:161], v[174:177], v[38:41]
	v_mfma_f32_16x16x32_bf16 v[30:33], v[150:153], v[182:185], v[30:33]
	v_mfma_f32_16x16x32_bf16 v[22:25], v[158:161], v[182:185], v[22:25]
	v_mfma_f32_16x16x32_bf16 v[14:17], v[150:153], v[190:193], v[14:17]
	v_mfma_f32_16x16x32_bf16 v[2:5], v[158:161], v[190:193], v[2:5]
	v_mfma_f32_16x16x32_bf16 v[62:65], v[154:157], v[170:173], v[62:65]
	v_mfma_f32_16x16x32_bf16 v[54:57], v[162:165], v[170:173], v[54:57]
	v_mfma_f32_16x16x32_bf16 v[46:49], v[154:157], v[178:181], v[46:49]
	v_mfma_f32_16x16x32_bf16 v[38:41], v[162:165], v[178:181], v[38:41]
	v_mfma_f32_16x16x32_bf16 v[30:33], v[154:157], v[186:189], v[30:33]
	v_mfma_f32_16x16x32_bf16 v[22:25], v[162:165], v[186:189], v[22:25]
	v_mfma_f32_16x16x32_bf16 v[14:17], v[154:157], v[210:213], v[14:17]
	v_mfma_f32_16x16x32_bf16 v[2:5], v[162:165], v[210:213], v[2:5]
	s_setprio 0
	s_barrier
	s_add_u32 s0, s0, 0x100
	s_addc_u32 s1, s1, 0
	s_cmp_ge_u32 s23, s94
	s_mov_b32 s10, s23
	s_cbranch_scc0 .LBB0_606

; #define PG8_STAGE(bufoff, gbase, voff) do { _Pragma("unroll") for (int _i = 0; _i < 2; ++_i) \
;         __builtin_amdgcn_global_load_lds((const unsigned*)((const char*)(gbase) + (voff)[_i]), (PG8_LAS unsigned*)(lds + (bufoff) + ldsw + _i * 8192), 16, 0, 0); } while (0)
; #define PG8_LDA(dst, b, h) do { _Pragma("unroll") for (int m = 0; m < 4; ++m) _Pragma("unroll") for (int k = 0; k < 2; ++k) dst[m][k] = *(const PG8_LAS bf16x8*)(lds + PG8_SA(b, h) + aoff + m * 2048 + k * 1024); } while (0)
; #define PG8_LDB(dst, b, h) do { _Pragma("unroll") for (int n = 0; n < 2; ++n) _Pragma("unroll") for (int k = 0; k < 2; ++k) dst[n][k] = *(const PG8_LAS bf16x8*)(lds + PG8_SB(b, h) + boff + n * 2048 + k * 1024); } while (0)
; #define PG8_WAIT_V(n) asm volatile("s_waitcnt vmcnt(" #n ")" ::: "memory")
; #define PG8_WAIT_L(n) asm volatile("s_waitcnt lgkmcnt(" #n ")" ::: "memory")
; template <class Epi, class Sched, bool ALIGN_EPI = false, bool SP2 = false>
; __device__ __forceinline__ void gemm_phase(PG8_LAS unsigned char* lds, const Gemm g, const Sched& S, const Epi& E, int tid_in) {
;     ...
;     f32x4 acc[2][2][4][2];
; #pragma unroll
;     for (int a = 0; a < 2; ++a)
; #pragma unroll
;         for (int b = 0; b < 2; ++b)
; #pragma unroll
;             for (int m = 0; m < 4; ++m)
; #pragma unroll
;                 for (int n = 0; n < 2; ++n) acc[a][b][m][n] = (f32x4){0.f, 0.f, 0.f, 0.f};
;     ...
;     for (;;) {
;         const bool has_next = S.next(ui + 1, nxt);
;         const char* nA = has_next ? (const char*)g.A + (size_t)nxt.pm * tstepA + (size_t)PG8_KOFF(nxt.pn) * kstep : cA; const char* nB = has_next ? (const char*)g.Bt + (size_t)nxt.pn * tstep + (size_t)PG8_KOFF(nxt.pn) * kstep : cB;
;         for (int t = 0; t < ntc; t += 2) {
;             const bool last = (t == ntc - 2);
;             const char* a1 = PG8_KA(cA, t + 1);
;             const char* a2 = last ? nA : PG8_KA(cA, t + 2); const char* b2 = last ? nB : cB + (size_t)(t + 2) * kstep;
;             const char* a3 = last ? PG8_KA(nA, 1) : PG8_KA(cA, t + 3); const char* b3 = b2 + kstep;
;             if (last && has_next) S.a_ready(nxt);
;             if constexpr (SP2) {
;             PG8_LDB(B0, 0, 0); PG8_LDB(B1, 0, 1); PG8_SCHED; PG8_LDA(At, 0, 0); PG8_STAGE(PG8_SA(1, 1), a1 + hstepA, voffA);
;             PG8_WAIT_V(8); PG8_WAIT_L(0); PG8_BAR; PG8_MMA(0, 0, At, B0); PG8_MMA(0, 1, At, B1); PG8_BAR; PG8_SCHED;
.LBB0_1179:
	s_add_u32 s21, s48, 0x80
	s_addc_u32 s53, s49, 0
	s_add_u32 s54, s8, 0x100
	s_addc_u32 s55, s9, 0
	s_mov_b32 s0, 0
	s_mov_b32 s56, s79
	s_waitcnt vmcnt(0)
	s_or_b32 s1, s0, 1
	s_cmp_ge_u32 s1, s84
	s_cselect_b32 s58, s86, 0
	s_cselect_b32 s59, s85, 0
	s_add_i32 s57, s0, 2
	s_cmp_ge_u32 s57, s84
	s_cselect_b32 s8, s86, 0
	s_cselect_b32 s1, s85, 0
	s_add_u32 s8, s6, s8
	s_addc_u32 s1, s7, s1
	s_add_u32 s8, s8, 0x100
	s_addc_u32 s1, s1, 0
	s_add_i32 s0, s0, 3
	s_cmp_ge_u32 s0, s84
	s_cselect_b32 s9, s86, 0
	s_cselect_b32 s0, s85, 0
	s_add_u32 s9, s6, s9
	s_addc_u32 s0, s7, s0
	s_add_u32 s62, s9, 0x180
	s_addc_u32 s0, s0, 0
	s_cmp_eq_u32 s56, 0
	s_cselect_b32 s9, s49, s1
	s_cselect_b32 s8, s48, s8
	s_cselect_b32 s61, s51, s55
	s_cselect_b32 s60, s50, s54
	s_cselect_b32 s1, s53, s0
	s_cselect_b32 s0, s21, s62
	s_add_i32 s62, 0, 0x10000
	v_add_u32_e32 v0, s62, v207
	s_add_i32 s63, 0, 0x14000
	ds_read_b128 v[132:135], v0
	ds_read_b128 v[136:139], v0 offset:1024
	ds_read_b128 v[140:143], v0 offset:2048
	ds_read_b128 v[144:147], v0 offset:3072
	v_add_u32_e32 v0, s63, v207
	ds_read_b128 v[148:151], v0
	ds_read_b128 v[152:155], v0 offset:1024
	ds_read_b128 v[156:159], v0 offset:2048
	ds_read_b128 v[160:163], v0 offset:3072
	v_lshl_add_u64 v[2:3], s[6:7], 0, v[180:181]
	v_lshl_add_u64 v[2:3], v[2:3], 0, s[58:59]
	s_add_i32 m0, s89, 0xc000
	ds_read_b128 v[164:167], v208
	ds_read_b128 v[168:171], v208 offset:1024
	ds_read_b128 v[184:187], v208 offset:2048
	ds_read_b128 v[188:191], v208 offset:3072
	ds_read_b128 v[196:199], v208 offset:4096
	ds_read_b128 v[200:203], v208 offset:5120
	ds_read_b128 v[210:213], v208 offset:6144
	ds_read_b128 v[214:217], v208 offset:7168
	global_load_lds_dwordx4 v[2:3], off
	v_lshl_add_u64 v[2:3], s[6:7], 0, v[182:183]
	v_lshl_add_u64 v[2:3], v[2:3], 0, s[58:59]
	s_add_i32 m0, s89, 0xe000
	s_nop 0
	global_load_lds_dwordx4 v[2:3], off
	s_waitcnt vmcnt(8)
	s_waitcnt lgkmcnt(0)
	s_barrier
	s_setprio 1
	s_waitcnt lgkmcnt(0)
	v_mfma_f32_16x16x32_bf16 v[124:127], v[132:135], v[164:167], 0
	v_mfma_f32_16x16x32_bf16 v[116:119], v[140:143], v[164:167], 0
	v_mfma_f32_16x16x32_bf16 v[108:111], v[132:135], v[184:187], 0
	v_mfma_f32_16x16x32_bf16 v[100:103], v[140:143], v[184:187], 0
	v_mfma_f32_16x16x32_bf16 v[92:95], v[132:135], v[196:199], 0
	v_mfma_f32_16x16x32_bf16 v[84:87], v[140:143], v[196:199], 0
	v_mfma_f32_16x16x32_bf16 v[76:79], v[132:135], v[210:213], 0
	v_mfma_f32_16x16x32_bf16 v[68:71], v[140:143], v[210:213], 0
	v_mfma_f32_16x16x32_bf16 v[124:127], v[136:139], v[168:171], v[124:127]
	v_mfma_f32_16x16x32_bf16 v[116:119], v[144:147], v[168:171], v[116:119]
	v_mfma_f32_16x16x32_bf16 v[108:111], v[136:139], v[188:191], v[108:111]
	v_mfma_f32_16x16x32_bf16 v[100:103], v[144:147], v[188:191], v[100:103]
	v_mfma_f32_16x16x32_bf16 v[92:95], v[136:139], v[200:203], v[92:95]
	v_mfma_f32_16x16x32_bf16 v[84:87], v[144:147], v[200:203], v[84:87]
	v_mfma_f32_16x16x32_bf16 v[76:79], v[136:139], v[214:217], v[76:79]
	v_mfma_f32_16x16x32_bf16 v[68:71], v[144:147], v[214:217], v[68:71]
	v_mfma_f32_16x16x32_bf16 v[128:131], v[148:151], v[164:167], 0
	v_mfma_f32_16x16x32_bf16 v[120:123], v[156:159], v[164:167], 0
	v_mfma_f32_16x16x32_bf16 v[112:115], v[148:151], v[184:187], 0
	v_mfma_f32_16x16x32_bf16 v[104:107], v[156:159], v[184:187], 0
	v_mfma_f32_16x16x32_bf16 v[96:99], v[148:151], v[196:199], 0
	v_mfma_f32_16x16x32_bf16 v[88:91], v[156:159], v[196:199], 0
	v_mfma_f32_16x16x32_bf16 v[80:83], v[148:151], v[210:213], 0
	v_mfma_f32_16x16x32_bf16 v[72:75], v[156:159], v[210:213], 0
	v_mfma_f32_16x16x32_bf16 v[128:131], v[152:155], v[168:171], v[128:131]
	v_mfma_f32_16x16x32_bf16 v[120:123], v[160:163], v[168:171], v[120:123]
	v_mfma_f32_16x16x32_bf16 v[112:115], v[152:155], v[188:191], v[112:115]
	v_mfma_f32_16x16x32_bf16 v[104:107], v[160:163], v[188:191], v[104:107]
	v_mfma_f32_16x16x32_bf16 v[96:99], v[152:155], v[200:203], v[96:99]
	v_mfma_f32_16x16x32_bf16 v[88:91], v[160:163], v[200:203], v[88:91]
	v_mfma_f32_16x16x32_bf16 v[80:83], v[152:155], v[214:217], v[80:83]
	v_mfma_f32_16x16x32_bf16 v[72:75], v[160:163], v[214:217], v[72:75]
	s_setprio 0
	s_barrier
	s_add_i32 s58, s62, s88
	v_lshl_add_u64 v[192:193], s[60:61], 0, v[178:179]
	s_mov_b32 m0, s58
	ds_read_b128 v[164:167], v208 offset:16384
	ds_read_b128 v[168:171], v208 offset:17408
	ds_read_b128 v[184:187], v208 offset:18432
	ds_read_b128 v[188:191], v208 offset:19456
	ds_read_b128 v[196:199], v208 offset:20480
	ds_read_b128 v[200:203], v208 offset:21504
	ds_read_b128 v[210:213], v208 offset:22528
	ds_read_b128 v[214:217], v208 offset:23552
	global_load_lds_dwordx4 v[192:193], off
	s_add_i32 m0, s58, 0x2000
	s_add_u32 s58, s60, s94
	v_lshl_add_u64 v[204:205], s[60:61], 0, v[174:175]
	s_addc_u32 s59, s61, 0
	s_add_i32 s60, s63, s88
	global_load_lds_dwordx4 v[204:205], off
	v_lshl_add_u64 v[218:219], s[58:59], 0, v[178:179]
	s_mov_b32 m0, s60
	v_lshl_add_u64 v[220:221], s[58:59], 0, v[174:175]
	global_load_lds_dwordx4 v[218:219], off
	s_add_i32 m0, s60, 0x2000
	v_lshl_add_u64 v[2:3], s[8:9], 0, v[176:177]
	global_load_lds_dwordx4 v[220:221], off
	s_mov_b32 m0, s89
	s_nop 0
	global_load_lds_dwordx4 v[2:3], off
	v_lshl_add_u64 v[2:3], s[8:9], 0, v[172:173]
	s_mov_b32 m0, s90
	s_nop 0
	global_load_lds_dwordx4 v[2:3], off
	s_waitcnt vmcnt(8)
	s_waitcnt lgkmcnt(0)
	s_barrier
; #define PG8_STAGE(bufoff, gbase, voff) do { _Pragma("unroll") for (int _i = 0; _i < 2; ++_i) \
;         __builtin_amdgcn_global_load_lds((const unsigned*)((const char*)(gbase) + (voff)[_i]), (PG8_LAS unsigned*)(lds + (bufoff) + ldsw + _i * 8192), 16, 0, 0); } while (0)
; #define PG8_LDA(dst, b, h) do { _Pragma("unroll") for (int m = 0; m < 4; ++m) _Pragma("unroll") for (int k = 0; k < 2; ++k) dst[m][k] = *(const PG8_LAS bf16x8*)(lds + PG8_SA(b, h) + aoff + m * 2048 + k * 1024); } while (0)
; #define PG8_LDB(dst, b, h) do { _Pragma("unroll") for (int n = 0; n < 2; ++n) _Pragma("unroll") for (int k = 0; k < 2; ++k) dst[n][k] = *(const PG8_LAS bf16x8*)(lds + PG8_SB(b, h) + boff + n * 2048 + k * 1024); } while (0)
; #define PG8_MMA(ai, bj, At, Bt) do { __builtin_amdgcn_s_setprio(1); _Pragma("unroll") for (int m = 0; m < 4; ++m) _Pragma("unroll") for (int n = 0; n < 2; ++n) _Pragma("unroll") for (int k = 0; k < 2; ++k) \
;         acc[ai][bj][m][n] = __builtin_amdgcn_mfma_f32_16x16x32_bf16(Bt[n][k], At[m][k], acc[ai][bj][m][n], 0, 0, 0); __builtin_amdgcn_s_setprio(0); } while (0)
; #define PG8_WAIT_V(n) asm volatile("s_waitcnt vmcnt(" #n ")" ::: "memory")
; #define PG8_WAIT_L(n) asm volatile("s_waitcnt lgkmcnt(" #n ")" ::: "memory")
; #define PG8_BAR __builtin_amdgcn_s_barrier()
; #define PG8_SCHED __builtin_amdgcn_sched_barrier(0)
; template <class Epi, class Sched, bool ALIGN_EPI = false, bool SP2 = false>
; __device__ __forceinline__ void gemm_phase(PG8_LAS unsigned char* lds, const Gemm g, const Sched& S, const Epi& E, int tid_in) {
;     ...
;             PG8_WAIT_V(8); PG8_WAIT_L(0); PG8_BAR; PG8_MMA(0, 0, At, B0); PG8_MMA(0, 1, At, B1); PG8_BAR; PG8_SCHED;
;             PG8_LDA(At, 0, 1); PG8_STAGE(PG8_SB(0, 0), b2, voffB); PG8_STAGE(PG8_SB(0, 1), b2 + hstep, voffB); PG8_STAGE(PG8_SA(0, 0), a2, voffA);
;             PG8_WAIT_V(8); PG8_WAIT_L(0); PG8_BAR; PG8_MMA(1, 0, At, B0); PG8_MMA(1, 1, At, B1); PG8_BAR; PG8_SCHED;
;             PG8_LDB(B0, 1, 0); PG8_LDB(B1, 1, 1); PG8_SCHED; PG8_LDA(At, 1, 0); PG8_STAGE(PG8_SA(0, 1), a2 + hstepA, voffA);
;             PG8_WAIT_V(8); PG8_WAIT_L(0); PG8_BAR; PG8_MMA(0, 0, At, B0); PG8_MMA(0, 1, At, B1); PG8_BAR; PG8_SCHED;
	s_setprio 1
	s_waitcnt lgkmcnt(0)
	v_mfma_f32_16x16x32_bf16 v[60:63], v[132:135], v[164:167], 0
	v_mfma_f32_16x16x32_bf16 v[52:55], v[140:143], v[164:167], 0
	v_mfma_f32_16x16x32_bf16 v[44:47], v[132:135], v[184:187], 0
	v_mfma_f32_16x16x32_bf16 v[36:39], v[140:143], v[184:187], 0
	v_mfma_f32_16x16x32_bf16 v[28:31], v[132:135], v[196:199], 0
	v_mfma_f32_16x16x32_bf16 v[20:23], v[140:143], v[196:199], 0
	v_mfma_f32_16x16x32_bf16 v[12:15], v[132:135], v[210:213], 0
	v_mfma_f32_16x16x32_bf16 v[2:5], v[140:143], v[210:213], 0
	v_mfma_f32_16x16x32_bf16 v[60:63], v[136:139], v[168:171], v[60:63]
	v_mfma_f32_16x16x32_bf16 v[52:55], v[144:147], v[168:171], v[52:55]
	v_mfma_f32_16x16x32_bf16 v[44:47], v[136:139], v[188:191], v[44:47]
	v_mfma_f32_16x16x32_bf16 v[36:39], v[144:147], v[188:191], v[36:39]
	v_mfma_f32_16x16x32_bf16 v[28:31], v[136:139], v[200:203], v[28:31]
	v_mfma_f32_16x16x32_bf16 v[20:23], v[144:147], v[200:203], v[20:23]
	v_mfma_f32_16x16x32_bf16 v[12:15], v[136:139], v[214:217], v[12:15]
	v_mfma_f32_16x16x32_bf16 v[2:5], v[144:147], v[214:217], v[2:5]
	v_mfma_f32_16x16x32_bf16 v[64:67], v[148:151], v[164:167], 0
	v_mfma_f32_16x16x32_bf16 v[56:59], v[156:159], v[164:167], 0
	v_mfma_f32_16x16x32_bf16 v[48:51], v[148:151], v[184:187], 0
	v_mfma_f32_16x16x32_bf16 v[40:43], v[156:159], v[184:187], 0
	v_mfma_f32_16x16x32_bf16 v[32:35], v[148:151], v[196:199], 0
	v_mfma_f32_16x16x32_bf16 v[24:27], v[156:159], v[196:199], 0
	v_mfma_f32_16x16x32_bf16 v[16:19], v[148:151], v[210:213], 0
	v_mfma_f32_16x16x32_bf16 v[6:9], v[156:159], v[210:213], 0
	v_mfma_f32_16x16x32_bf16 v[64:67], v[152:155], v[168:171], v[64:67]
	v_mfma_f32_16x16x32_bf16 v[56:59], v[160:163], v[168:171], v[56:59]
	v_mfma_f32_16x16x32_bf16 v[48:51], v[152:155], v[188:191], v[48:51]
	v_mfma_f32_16x16x32_bf16 v[40:43], v[160:163], v[188:191], v[40:43]
	v_mfma_f32_16x16x32_bf16 v[32:35], v[152:155], v[200:203], v[32:35]
	v_mfma_f32_16x16x32_bf16 v[24:27], v[160:163], v[200:203], v[24:27]
	v_mfma_f32_16x16x32_bf16 v[16:19], v[152:155], v[214:217], v[16:19]
	v_mfma_f32_16x16x32_bf16 v[8:11], v[160:163], v[214:217], v[6:9]
	s_setprio 0
	s_barrier
	s_add_i32 s58, 0, 0x18000
	v_add_u32_e32 v0, s58, v207
	s_add_i32 s59, 0, 0x1c000
	ds_read_b128 v[132:135], v0
	ds_read_b128 v[136:139], v0 offset:1024
	ds_read_b128 v[140:143], v0 offset:2048
	ds_read_b128 v[144:147], v0 offset:3072
	v_add_u32_e32 v0, s59, v207
	ds_read_b128 v[148:151], v0
	ds_read_b128 v[152:155], v0 offset:1024
	ds_read_b128 v[156:159], v0 offset:2048
	ds_read_b128 v[160:163], v0 offset:3072
	s_add_u32 s8, s8, s94
	s_addc_u32 s9, s9, 0
	s_mov_b32 m0, s91
	v_lshl_add_u64 v[6:7], s[8:9], 0, v[176:177]
	ds_read_b128 v[164:167], v208 offset:32768
	ds_read_b128 v[168:171], v208 offset:33792
	ds_read_b128 v[184:187], v208 offset:34816
	ds_read_b128 v[188:191], v208 offset:35840
	ds_read_b128 v[196:199], v208 offset:36864
	ds_read_b128 v[200:203], v208 offset:37888
	ds_read_b128 v[210:213], v208 offset:38912
	ds_read_b128 v[214:217], v208 offset:39936
	global_load_lds_dwordx4 v[6:7], off
	v_lshl_add_u64 v[6:7], s[8:9], 0, v[172:173]
	s_mov_b32 m0, s92
	s_nop 0
	global_load_lds_dwordx4 v[6:7], off
	s_waitcnt vmcnt(8)
	s_waitcnt lgkmcnt(0)
	s_barrier
	s_setprio 1
	s_waitcnt lgkmcnt(0)
	v_mfma_f32_16x16x32_bf16 v[124:127], v[132:135], v[164:167], v[124:127]
	v_mfma_f32_16x16x32_bf16 v[116:119], v[140:143], v[164:167], v[116:119]
	v_mfma_f32_16x16x32_bf16 v[108:111], v[132:135], v[184:187], v[108:111]
	v_mfma_f32_16x16x32_bf16 v[100:103], v[140:143], v[184:187], v[100:103]
	v_mfma_f32_16x16x32_bf16 v[92:95], v[132:135], v[196:199], v[92:95]
	v_mfma_f32_16x16x32_bf16 v[84:87], v[140:143], v[196:199], v[84:87]
	v_mfma_f32_16x16x32_bf16 v[76:79], v[132:135], v[210:213], v[76:79]
	v_mfma_f32_16x16x32_bf16 v[68:71], v[140:143], v[210:213], v[68:71]
	v_mfma_f32_16x16x32_bf16 v[124:127], v[136:139], v[168:171], v[124:127]
	v_mfma_f32_16x16x32_bf16 v[116:119], v[144:147], v[168:171], v[116:119]
	v_mfma_f32_16x16x32_bf16 v[108:111], v[136:139], v[188:191], v[108:111]
	v_mfma_f32_16x16x32_bf16 v[100:103], v[144:147], v[188:191], v[100:103]
	v_mfma_f32_16x16x32_bf16 v[92:95], v[136:139], v[200:203], v[92:95]
	v_mfma_f32_16x16x32_bf16 v[84:87], v[144:147], v[200:203], v[84:87]
	v_mfma_f32_16x16x32_bf16 v[76:79], v[136:139], v[214:217], v[76:79]
	v_mfma_f32_16x16x32_bf16 v[68:71], v[144:147], v[214:217], v[68:71]
	v_mfma_f32_16x16x32_bf16 v[128:131], v[148:151], v[164:167], v[128:131]
	v_mfma_f32_16x16x32_bf16 v[120:123], v[156:159], v[164:167], v[120:123]
	v_mfma_f32_16x16x32_bf16 v[112:115], v[148:151], v[184:187], v[112:115]
	v_mfma_f32_16x16x32_bf16 v[104:107], v[156:159], v[184:187], v[104:107]
	v_mfma_f32_16x16x32_bf16 v[96:99], v[148:151], v[196:199], v[96:99]
	v_mfma_f32_16x16x32_bf16 v[88:91], v[156:159], v[196:199], v[88:91]
	v_mfma_f32_16x16x32_bf16 v[80:83], v[148:151], v[210:213], v[80:83]
	v_mfma_f32_16x16x32_bf16 v[72:75], v[156:159], v[210:213], v[72:75]
	v_mfma_f32_16x16x32_bf16 v[128:131], v[152:155], v[168:171], v[128:131]
	v_mfma_f32_16x16x32_bf16 v[120:123], v[160:163], v[168:171], v[120:123]
	v_mfma_f32_16x16x32_bf16 v[112:115], v[152:155], v[188:191], v[112:115]
	v_mfma_f32_16x16x32_bf16 v[104:107], v[160:163], v[188:191], v[104:107]
	v_mfma_f32_16x16x32_bf16 v[96:99], v[152:155], v[200:203], v[96:99]
	v_mfma_f32_16x16x32_bf16 v[88:91], v[160:163], v[200:203], v[88:91]
	v_mfma_f32_16x16x32_bf16 v[80:83], v[152:155], v[214:217], v[80:83]
	v_mfma_f32_16x16x32_bf16 v[72:75], v[160:163], v[214:217], v[72:75]
	s_setprio 0
	s_barrier
; #define PG8_STAGE(bufoff, gbase, voff) do { _Pragma("unroll") for (int _i = 0; _i < 2; ++_i) \
;         __builtin_amdgcn_global_load_lds((const unsigned*)((const char*)(gbase) + (voff)[_i]), (PG8_LAS unsigned*)(lds + (bufoff) + ldsw + _i * 8192), 16, 0, 0); } while (0)
; #define PG8_LDA(dst, b, h) do { _Pragma("unroll") for (int m = 0; m < 4; ++m) _Pragma("unroll") for (int k = 0; k < 2; ++k) dst[m][k] = *(const PG8_LAS bf16x8*)(lds + PG8_SA(b, h) + aoff + m * 2048 + k * 1024); } while (0)
; #define PG8_MMA(ai, bj, At, Bt) do { __builtin_amdgcn_s_setprio(1); _Pragma("unroll") for (int m = 0; m < 4; ++m) _Pragma("unroll") for (int n = 0; n < 2; ++n) _Pragma("unroll") for (int k = 0; k < 2; ++k) \
;         acc[ai][bj][m][n] = __builtin_amdgcn_mfma_f32_16x16x32_bf16(Bt[n][k], At[m][k], acc[ai][bj][m][n], 0, 0, 0); __builtin_amdgcn_s_setprio(0); } while (0)
; #define PG8_WAIT_V(n) asm volatile("s_waitcnt vmcnt(" #n ")" ::: "memory")
; #define PG8_WAIT_L(n) asm volatile("s_waitcnt lgkmcnt(" #n ")" ::: "memory")
; #define PG8_BAR __builtin_amdgcn_s_barrier()
; #define PG8_SCHED __builtin_amdgcn_sched_barrier(0)
; template <class Epi, class Sched, bool ALIGN_EPI = false, bool SP2 = false>
; __device__ __forceinline__ void gemm_phase(PG8_LAS unsigned char* lds, const Gemm g, const Sched& S, const Epi& E, int tid_in) {
;     ...
;         for (int t = 0; t < ntc; t += 2) {
;     ...
;             PG8_LDA(At, 1, 1); PG8_STAGE(PG8_SB(1, 0), b3, voffB); PG8_STAGE(PG8_SB(1, 1), b3 + hstep, voffB); PG8_STAGE(PG8_SA(1, 0), a3, voffA);
;             PG8_WAIT_V(8); PG8_WAIT_L(0); PG8_BAR; PG8_MMA(1, 0, At, B0); PG8_MMA(1, 1, At, B1); PG8_BAR; PG8_SCHED;
	s_add_i32 s8, s58, s88
	v_lshl_add_u64 v[6:7], v[192:193], 0, s[96:97]
	s_mov_b32 m0, s8
	ds_read_b128 v[164:167], v208 offset:49152
	ds_read_b128 v[168:171], v208 offset:50176
	ds_read_b128 v[184:187], v208 offset:51200
	ds_read_b128 v[188:191], v208 offset:52224
	ds_read_b128 v[196:199], v208 offset:53248
	ds_read_b128 v[200:203], v208 offset:54272
	ds_read_b128 v[210:213], v208 offset:55296
	ds_read_b128 v[214:217], v208 offset:56320
	global_load_lds_dwordx4 v[6:7], off
	v_lshl_add_u64 v[6:7], v[204:205], 0, s[96:97]
	s_add_i32 m0, s8, 0x2000
	s_add_i32 s8, s59, s88
	global_load_lds_dwordx4 v[6:7], off
	v_lshl_add_u64 v[6:7], v[218:219], 0, s[96:97]
	s_mov_b32 m0, s8
	s_nop 0
	global_load_lds_dwordx4 v[6:7], off
	v_lshl_add_u64 v[6:7], v[220:221], 0, s[96:97]
	s_add_i32 m0, s8, 0x2000
	s_nop 0
	global_load_lds_dwordx4 v[6:7], off
	v_lshl_add_u64 v[6:7], s[0:1], 0, v[176:177]
	s_mov_b32 m0, s93
	s_nop 0
	global_load_lds_dwordx4 v[6:7], off
	v_lshl_add_u64 v[6:7], s[0:1], 0, v[172:173]
	s_mov_b32 m0, s78
	s_nop 0
	global_load_lds_dwordx4 v[6:7], off
	s_waitcnt vmcnt(8)
	s_waitcnt lgkmcnt(0)
	s_barrier
	s_setprio 1
	s_waitcnt lgkmcnt(0)
	v_mfma_f32_16x16x32_bf16 v[60:63], v[132:135], v[164:167], v[60:63]
	v_mfma_f32_16x16x32_bf16 v[52:55], v[140:143], v[164:167], v[52:55]
	v_mfma_f32_16x16x32_bf16 v[44:47], v[132:135], v[184:187], v[44:47]
	v_mfma_f32_16x16x32_bf16 v[36:39], v[140:143], v[184:187], v[36:39]
	v_mfma_f32_16x16x32_bf16 v[28:31], v[132:135], v[196:199], v[28:31]
	v_mfma_f32_16x16x32_bf16 v[20:23], v[140:143], v[196:199], v[20:23]
	v_mfma_f32_16x16x32_bf16 v[12:15], v[132:135], v[210:213], v[12:15]
	v_mfma_f32_16x16x32_bf16 v[2:5], v[140:143], v[210:213], v[2:5]
	v_mfma_f32_16x16x32_bf16 v[60:63], v[136:139], v[168:171], v[60:63]
	v_mfma_f32_16x16x32_bf16 v[52:55], v[144:147], v[168:171], v[52:55]
	v_mfma_f32_16x16x32_bf16 v[44:47], v[136:139], v[188:191], v[44:47]
	v_mfma_f32_16x16x32_bf16 v[36:39], v[144:147], v[188:191], v[36:39]
	v_mfma_f32_16x16x32_bf16 v[28:31], v[136:139], v[200:203], v[28:31]
	v_mfma_f32_16x16x32_bf16 v[20:23], v[144:147], v[200:203], v[20:23]
	v_mfma_f32_16x16x32_bf16 v[12:15], v[136:139], v[214:217], v[12:15]
	v_mfma_f32_16x16x32_bf16 v[4:7], v[144:147], v[214:217], v[2:5]
	v_mfma_f32_16x16x32_bf16 v[64:67], v[148:151], v[164:167], v[64:67]
	v_mfma_f32_16x16x32_bf16 v[56:59], v[156:159], v[164:167], v[56:59]
	v_mfma_f32_16x16x32_bf16 v[48:51], v[148:151], v[184:187], v[48:51]
	v_mfma_f32_16x16x32_bf16 v[40:43], v[156:159], v[184:187], v[40:43]
	v_mfma_f32_16x16x32_bf16 v[32:35], v[148:151], v[196:199], v[32:35]
	v_mfma_f32_16x16x32_bf16 v[24:27], v[156:159], v[196:199], v[24:27]
	v_mfma_f32_16x16x32_bf16 v[16:19], v[148:151], v[210:213], v[16:19]
	v_mfma_f32_16x16x32_bf16 v[8:11], v[156:159], v[210:213], v[8:11]
	v_mfma_f32_16x16x32_bf16 v[64:67], v[152:155], v[168:171], v[64:67]
	v_mfma_f32_16x16x32_bf16 v[56:59], v[160:163], v[168:171], v[56:59]
	v_mfma_f32_16x16x32_bf16 v[48:51], v[152:155], v[188:191], v[48:51]
	v_mfma_f32_16x16x32_bf16 v[40:43], v[160:163], v[188:191], v[40:43]
	v_mfma_f32_16x16x32_bf16 v[32:35], v[152:155], v[200:203], v[32:35]
	v_mfma_f32_16x16x32_bf16 v[24:27], v[160:163], v[200:203], v[24:27]
	v_mfma_f32_16x16x32_bf16 v[16:19], v[152:155], v[214:217], v[16:19]
	v_mfma_f32_16x16x32_bf16 v[8:11], v[160:163], v[214:217], v[8:11]
	s_setprio 0
	s_barrier
	s_add_u32 s6, s6, 0x100
	s_addc_u32 s7, s7, 0
	s_add_u32 s54, s54, 0x100
	s_addc_u32 s55, s55, 0
	s_add_i32 s56, s56, -2
	s_cmp_ge_u32 s57, s18
	s_mov_b32 s0, s57
	s_cbranch_scc1 .Lzk1_exit
.LBB0_1180:
	s_or_b32 s1, s0, 1
	s_cmp_ge_u32 s1, s84
	s_cselect_b32 s58, s86, 0
	s_cselect_b32 s59, s85, 0
	s_add_i32 s57, s0, 2
	s_cmp_ge_u32 s57, s84
	s_cselect_b32 s8, s86, 0
	s_cselect_b32 s1, s85, 0
	s_add_u32 s8, s6, s8
	s_addc_u32 s1, s7, s1
	s_add_u32 s8, s8, 0x100
	s_addc_u32 s1, s1, 0
	s_add_i32 s0, s0, 3
	s_cmp_ge_u32 s0, s84
	s_cselect_b32 s9, s86, 0
	s_cselect_b32 s0, s85, 0
	s_add_u32 s9, s6, s9
	s_addc_u32 s0, s7, s0
	s_add_u32 s62, s9, 0x180
	s_addc_u32 s0, s0, 0
	s_cmp_eq_u32 s56, 0
	s_cselect_b32 s9, s49, s1
	s_cselect_b32 s8, s48, s8
	s_cselect_b32 s61, s51, s55
	s_cselect_b32 s60, s50, s54
	s_cselect_b32 s1, s53, s0
	s_cselect_b32 s0, s21, s62
	s_add_i32 s62, 0, 0x10000
	v_add_u32_e32 v0, s62, v207
	s_add_i32 s63, 0, 0x14000
	ds_read_b128 v[132:135], v0
	ds_read_b128 v[136:139], v0 offset:1024
	ds_read_b128 v[140:143], v0 offset:2048
	ds_read_b128 v[144:147], v0 offset:3072
	v_add_u32_e32 v0, s63, v207
	ds_read_b128 v[148:151], v0
	ds_read_b128 v[152:155], v0 offset:1024
	ds_read_b128 v[156:159], v0 offset:2048
	ds_read_b128 v[160:163], v0 offset:3072
	v_lshl_add_u64 v[2:3], s[6:7], 0, v[180:181]
	v_lshl_add_u64 v[2:3], v[2:3], 0, s[58:59]
	s_add_i32 m0, s89, 0xc000
	ds_read_b128 v[164:167], v208
	ds_read_b128 v[168:171], v208 offset:1024
	ds_read_b128 v[184:187], v208 offset:2048
	ds_read_b128 v[188:191], v208 offset:3072
	ds_read_b128 v[196:199], v208 offset:4096
	ds_read_b128 v[200:203], v208 offset:5120
	ds_read_b128 v[210:213], v208 offset:6144
	ds_read_b128 v[214:217], v208 offset:7168
	global_load_lds_dwordx4 v[2:3], off
	v_lshl_add_u64 v[2:3], s[6:7], 0, v[182:183]
	v_lshl_add_u64 v[2:3], v[2:3], 0, s[58:59]
	s_add_i32 m0, s89, 0xe000
	s_nop 0
	global_load_lds_dwordx4 v[2:3], off
	s_waitcnt vmcnt(8)
	s_waitcnt lgkmcnt(0)
	s_barrier
; #define PG8_STAGE(bufoff, gbase, voff) do { _Pragma("unroll") for (int _i = 0; _i < 2; ++_i) \
;         __builtin_amdgcn_global_load_lds((const unsigned*)((const char*)(gbase) + (voff)[_i]), (PG8_LAS unsigned*)(lds + (bufoff) + ldsw + _i * 8192), 16, 0, 0); } while (0)
; #define PG8_LDA(dst, b, h) do { _Pragma("unroll") for (int m = 0; m < 4; ++m) _Pragma("unroll") for (int k = 0; k < 2; ++k) dst[m][k] = *(const PG8_LAS bf16x8*)(lds + PG8_SA(b, h) + aoff + m * 2048 + k * 1024); } while (0)
; #define PG8_LDB(dst, b, h) do { _Pragma("unroll") for (int n = 0; n < 2; ++n) _Pragma("unroll") for (int k = 0; k < 2; ++k) dst[n][k] = *(const PG8_LAS bf16x8*)(lds + PG8_SB(b, h) + boff + n * 2048 + k * 1024); } while (0)
; #define PG8_MMA(ai, bj, At, Bt) do { __builtin_amdgcn_s_setprio(1); _Pragma("unroll") for (int m = 0; m < 4; ++m) _Pragma("unroll") for (int n = 0; n < 2; ++n) _Pragma("unroll") for (int k = 0; k < 2; ++k) \
;         acc[ai][bj][m][n] = __builtin_amdgcn_mfma_f32_16x16x32_bf16(Bt[n][k], At[m][k], acc[ai][bj][m][n], 0, 0, 0); __builtin_amdgcn_s_setprio(0); } while (0)
; #define PG8_WAIT_V(n) asm volatile("s_waitcnt vmcnt(" #n ")" ::: "memory")
; #define PG8_WAIT_L(n) asm volatile("s_waitcnt lgkmcnt(" #n ")" ::: "memory")
; #define PG8_BAR __builtin_amdgcn_s_barrier()
; #define PG8_SCHED __builtin_amdgcn_sched_barrier(0)
; template <class Epi, class Sched, bool ALIGN_EPI = false, bool SP2 = false>
; __device__ __forceinline__ void gemm_phase(PG8_LAS unsigned char* lds, const Gemm g, const Sched& S, const Epi& E, int tid_in) {
;     ...
;             PG8_LDB(B0, 0, 0); PG8_LDB(B1, 0, 1); PG8_SCHED; PG8_LDA(At, 0, 0); PG8_STAGE(PG8_SA(1, 1), a1 + hstepA, voffA);
;             PG8_WAIT_V(8); PG8_WAIT_L(0); PG8_BAR; PG8_MMA(0, 0, At, B0); PG8_MMA(0, 1, At, B1); PG8_BAR; PG8_SCHED;
;             PG8_LDA(At, 0, 1); PG8_STAGE(PG8_SB(0, 0), b2, voffB); PG8_STAGE(PG8_SB(0, 1), b2 + hstep, voffB); PG8_STAGE(PG8_SA(0, 0), a2, voffA);
;             PG8_WAIT_V(8); PG8_WAIT_L(0); PG8_BAR; PG8_MMA(1, 0, At, B0); PG8_MMA(1, 1, At, B1); PG8_BAR; PG8_SCHED;
;             PG8_LDB(B0, 1, 0); PG8_LDB(B1, 1, 1); PG8_SCHED; PG8_LDA(At, 1, 0); PG8_STAGE(PG8_SA(0, 1), a2 + hstepA, voffA);
;             PG8_WAIT_V(8); PG8_WAIT_L(0); PG8_BAR; PG8_MMA(0, 0, At, B0); PG8_MMA(0, 1, At, B1); PG8_BAR; PG8_SCHED;
	s_setprio 1
	s_waitcnt lgkmcnt(0)
	v_mfma_f32_16x16x32_bf16 v[124:127], v[132:135], v[164:167], v[124:127]
	v_mfma_f32_16x16x32_bf16 v[116:119], v[140:143], v[164:167], v[116:119]
	v_mfma_f32_16x16x32_bf16 v[108:111], v[132:135], v[184:187], v[108:111]
	v_mfma_f32_16x16x32_bf16 v[100:103], v[140:143], v[184:187], v[100:103]
	v_mfma_f32_16x16x32_bf16 v[92:95], v[132:135], v[196:199], v[92:95]
	v_mfma_f32_16x16x32_bf16 v[84:87], v[140:143], v[196:199], v[84:87]
	v_mfma_f32_16x16x32_bf16 v[76:79], v[132:135], v[210:213], v[76:79]
	v_mfma_f32_16x16x32_bf16 v[68:71], v[140:143], v[210:213], v[68:71]
	v_mfma_f32_16x16x32_bf16 v[124:127], v[136:139], v[168:171], v[124:127]
	v_mfma_f32_16x16x32_bf16 v[116:119], v[144:147], v[168:171], v[116:119]
	v_mfma_f32_16x16x32_bf16 v[108:111], v[136:139], v[188:191], v[108:111]
	v_mfma_f32_16x16x32_bf16 v[100:103], v[144:147], v[188:191], v[100:103]
	v_mfma_f32_16x16x32_bf16 v[92:95], v[136:139], v[200:203], v[92:95]
	v_mfma_f32_16x16x32_bf16 v[84:87], v[144:147], v[200:203], v[84:87]
	v_mfma_f32_16x16x32_bf16 v[76:79], v[136:139], v[214:217], v[76:79]
	v_mfma_f32_16x16x32_bf16 v[68:71], v[144:147], v[214:217], v[68:71]
	v_mfma_f32_16x16x32_bf16 v[128:131], v[148:151], v[164:167], v[128:131]
	v_mfma_f32_16x16x32_bf16 v[120:123], v[156:159], v[164:167], v[120:123]
	v_mfma_f32_16x16x32_bf16 v[112:115], v[148:151], v[184:187], v[112:115]
	v_mfma_f32_16x16x32_bf16 v[104:107], v[156:159], v[184:187], v[104:107]
	v_mfma_f32_16x16x32_bf16 v[96:99], v[148:151], v[196:199], v[96:99]
	v_mfma_f32_16x16x32_bf16 v[88:91], v[156:159], v[196:199], v[88:91]
	v_mfma_f32_16x16x32_bf16 v[80:83], v[148:151], v[210:213], v[80:83]
	v_mfma_f32_16x16x32_bf16 v[72:75], v[156:159], v[210:213], v[72:75]
	v_mfma_f32_16x16x32_bf16 v[128:131], v[152:155], v[168:171], v[128:131]
	v_mfma_f32_16x16x32_bf16 v[120:123], v[160:163], v[168:171], v[120:123]
	v_mfma_f32_16x16x32_bf16 v[112:115], v[152:155], v[188:191], v[112:115]
	v_mfma_f32_16x16x32_bf16 v[104:107], v[160:163], v[188:191], v[104:107]
	v_mfma_f32_16x16x32_bf16 v[96:99], v[152:155], v[200:203], v[96:99]
	v_mfma_f32_16x16x32_bf16 v[88:91], v[160:163], v[200:203], v[88:91]
	v_mfma_f32_16x16x32_bf16 v[80:83], v[152:155], v[214:217], v[80:83]
	v_mfma_f32_16x16x32_bf16 v[72:75], v[160:163], v[214:217], v[72:75]
	s_setprio 0
	s_barrier
	s_add_i32 s58, s62, s88
	v_lshl_add_u64 v[192:193], s[60:61], 0, v[178:179]
	s_mov_b32 m0, s58
	ds_read_b128 v[164:167], v208 offset:16384
	ds_read_b128 v[168:171], v208 offset:17408
	ds_read_b128 v[184:187], v208 offset:18432
	ds_read_b128 v[188:191], v208 offset:19456
	ds_read_b128 v[196:199], v208 offset:20480
	ds_read_b128 v[200:203], v208 offset:21504
	ds_read_b128 v[210:213], v208 offset:22528
	ds_read_b128 v[214:217], v208 offset:23552
	global_load_lds_dwordx4 v[192:193], off
	s_add_i32 m0, s58, 0x2000
	s_add_u32 s58, s60, s94
	v_lshl_add_u64 v[204:205], s[60:61], 0, v[174:175]
	s_addc_u32 s59, s61, 0
	s_add_i32 s60, s63, s88
	global_load_lds_dwordx4 v[204:205], off
	v_lshl_add_u64 v[218:219], s[58:59], 0, v[178:179]
	s_mov_b32 m0, s60
	v_lshl_add_u64 v[220:221], s[58:59], 0, v[174:175]
	global_load_lds_dwordx4 v[218:219], off
	s_add_i32 m0, s60, 0x2000
	v_lshl_add_u64 v[2:3], s[8:9], 0, v[176:177]
	global_load_lds_dwordx4 v[220:221], off
	s_mov_b32 m0, s89
	s_nop 0
	global_load_lds_dwordx4 v[2:3], off
	v_lshl_add_u64 v[2:3], s[8:9], 0, v[172:173]
	s_mov_b32 m0, s90
	s_nop 0
	global_load_lds_dwordx4 v[2:3], off
	s_waitcnt vmcnt(8)
	s_waitcnt lgkmcnt(0)
	s_barrier
	s_setprio 1
	s_waitcnt lgkmcnt(0)
	v_mfma_f32_16x16x32_bf16 v[60:63], v[132:135], v[164:167], v[60:63]
	v_mfma_f32_16x16x32_bf16 v[52:55], v[140:143], v[164:167], v[52:55]
	v_mfma_f32_16x16x32_bf16 v[44:47], v[132:135], v[184:187], v[44:47]
	v_mfma_f32_16x16x32_bf16 v[36:39], v[140:143], v[184:187], v[36:39]
	v_mfma_f32_16x16x32_bf16 v[28:31], v[132:135], v[196:199], v[28:31]
	v_mfma_f32_16x16x32_bf16 v[20:23], v[140:143], v[196:199], v[20:23]
	v_mfma_f32_16x16x32_bf16 v[12:15], v[132:135], v[210:213], v[12:15]
	v_mfma_f32_16x16x32_bf16 v[2:5], v[140:143], v[210:213], v[4:7]
	v_mfma_f32_16x16x32_bf16 v[60:63], v[136:139], v[168:171], v[60:63]
	v_mfma_f32_16x16x32_bf16 v[52:55], v[144:147], v[168:171], v[52:55]
	v_mfma_f32_16x16x32_bf16 v[44:47], v[136:139], v[188:191], v[44:47]
	v_mfma_f32_16x16x32_bf16 v[36:39], v[144:147], v[188:191], v[36:39]
	v_mfma_f32_16x16x32_bf16 v[28:31], v[136:139], v[200:203], v[28:31]
	v_mfma_f32_16x16x32_bf16 v[20:23], v[144:147], v[200:203], v[20:23]
	v_mfma_f32_16x16x32_bf16 v[12:15], v[136:139], v[214:217], v[12:15]
	v_mfma_f32_16x16x32_bf16 v[2:5], v[144:147], v[214:217], v[2:5]
	v_mfma_f32_16x16x32_bf16 v[64:67], v[148:151], v[164:167], v[64:67]
	v_mfma_f32_16x16x32_bf16 v[56:59], v[156:159], v[164:167], v[56:59]
	v_mfma_f32_16x16x32_bf16 v[48:51], v[148:151], v[184:187], v[48:51]
	v_mfma_f32_16x16x32_bf16 v[40:43], v[156:159], v[184:187], v[40:43]
	v_mfma_f32_16x16x32_bf16 v[32:35], v[148:151], v[196:199], v[32:35]
	v_mfma_f32_16x16x32_bf16 v[24:27], v[156:159], v[196:199], v[24:27]
	v_mfma_f32_16x16x32_bf16 v[16:19], v[148:151], v[210:213], v[16:19]
	v_mfma_f32_16x16x32_bf16 v[6:9], v[156:159], v[210:213], v[8:11]
	v_mfma_f32_16x16x32_bf16 v[64:67], v[152:155], v[168:171], v[64:67]
	v_mfma_f32_16x16x32_bf16 v[56:59], v[160:163], v[168:171], v[56:59]
	v_mfma_f32_16x16x32_bf16 v[48:51], v[152:155], v[188:191], v[48:51]
	v_mfma_f32_16x16x32_bf16 v[40:43], v[160:163], v[188:191], v[40:43]
	v_mfma_f32_16x16x32_bf16 v[32:35], v[152:155], v[200:203], v[32:35]
	v_mfma_f32_16x16x32_bf16 v[24:27], v[160:163], v[200:203], v[24:27]
	v_mfma_f32_16x16x32_bf16 v[16:19], v[152:155], v[214:217], v[16:19]
	v_mfma_f32_16x16x32_bf16 v[8:11], v[160:163], v[214:217], v[6:9]
	s_setprio 0
	s_barrier
; #define PG8_STAGE(bufoff, gbase, voff) do { _Pragma("unroll") for (int _i = 0; _i < 2; ++_i) \
;         __builtin_amdgcn_global_load_lds((const unsigned*)((const char*)(gbase) + (voff)[_i]), (PG8_LAS unsigned*)(lds + (bufoff) + ldsw + _i * 8192), 16, 0, 0); } while (0)
; #define PG8_LDA(dst, b, h) do { _Pragma("unroll") for (int m = 0; m < 4; ++m) _Pragma("unroll") for (int k = 0; k < 2; ++k) dst[m][k] = *(const PG8_LAS bf16x8*)(lds + PG8_SA(b, h) + aoff + m * 2048 + k * 1024); } while (0)
; #define PG8_LDB(dst, b, h) do { _Pragma("unroll") for (int n = 0; n < 2; ++n) _Pragma("unroll") for (int k = 0; k < 2; ++k) dst[n][k] = *(const PG8_LAS bf16x8*)(lds + PG8_SB(b, h) + boff + n * 2048 + k * 1024); } while (0)
; #define PG8_MMA(ai, bj, At, Bt) do { __builtin_amdgcn_s_setprio(1); _Pragma("unroll") for (int m = 0; m < 4; ++m) _Pragma("unroll") for (int n = 0; n < 2; ++n) _Pragma("unroll") for (int k = 0; k < 2; ++k) \
;         acc[ai][bj][m][n] = __builtin_amdgcn_mfma_f32_16x16x32_bf16(Bt[n][k], At[m][k], acc[ai][bj][m][n], 0, 0, 0); __builtin_amdgcn_s_setprio(0); } while (0)
; #define PG8_WAIT_V(n) asm volatile("s_waitcnt vmcnt(" #n ")" ::: "memory")
; #define PG8_WAIT_L(n) asm volatile("s_waitcnt lgkmcnt(" #n ")" ::: "memory")
; #define PG8_BAR __builtin_amdgcn_s_barrier()
; #define PG8_SCHED __builtin_amdgcn_sched_barrier(0)
; template <class Epi, class Sched, bool ALIGN_EPI = false, bool SP2 = false>
; __device__ __forceinline__ void gemm_phase(PG8_LAS unsigned char* lds, const Gemm g, const Sched& S, const Epi& E, int tid_in) {
;     ...
;         for (int t = 0; t < ntc; t += 2) {
;     ...
;             PG8_LDB(B0, 1, 0); PG8_LDB(B1, 1, 1); PG8_SCHED; PG8_LDA(At, 1, 0); PG8_STAGE(PG8_SA(0, 1), a2 + hstepA, voffA);
;             PG8_WAIT_V(8); PG8_WAIT_L(0); PG8_BAR; PG8_MMA(0, 0, At, B0); PG8_MMA(0, 1, At, B1); PG8_BAR; PG8_SCHED;
;             PG8_LDA(At, 1, 1); PG8_STAGE(PG8_SB(1, 0), b3, voffB); PG8_STAGE(PG8_SB(1, 1), b3 + hstep, voffB); PG8_STAGE(PG8_SA(1, 0), a3, voffA);
;             PG8_WAIT_V(8); PG8_WAIT_L(0); PG8_BAR; PG8_MMA(1, 0, At, B0); PG8_MMA(1, 1, At, B1); PG8_BAR; PG8_SCHED;
	s_add_i32 s58, 0, 0x18000
	v_add_u32_e32 v0, s58, v207
	s_add_i32 s59, 0, 0x1c000
	ds_read_b128 v[132:135], v0
	ds_read_b128 v[136:139], v0 offset:1024
	ds_read_b128 v[140:143], v0 offset:2048
	ds_read_b128 v[144:147], v0 offset:3072
	v_add_u32_e32 v0, s59, v207
	ds_read_b128 v[148:151], v0
	ds_read_b128 v[152:155], v0 offset:1024
	ds_read_b128 v[156:159], v0 offset:2048
	ds_read_b128 v[160:163], v0 offset:3072
	s_add_u32 s8, s8, s94
	s_addc_u32 s9, s9, 0
	s_mov_b32 m0, s91
	v_lshl_add_u64 v[6:7], s[8:9], 0, v[176:177]
	ds_read_b128 v[164:167], v208 offset:32768
	ds_read_b128 v[168:171], v208 offset:33792
	ds_read_b128 v[184:187], v208 offset:34816
	ds_read_b128 v[188:191], v208 offset:35840
	ds_read_b128 v[196:199], v208 offset:36864
	ds_read_b128 v[200:203], v208 offset:37888
	ds_read_b128 v[210:213], v208 offset:38912
	ds_read_b128 v[214:217], v208 offset:39936
	global_load_lds_dwordx4 v[6:7], off
	v_lshl_add_u64 v[6:7], s[8:9], 0, v[172:173]
	s_mov_b32 m0, s92
	s_nop 0
	global_load_lds_dwordx4 v[6:7], off
	s_waitcnt vmcnt(8)
	s_waitcnt lgkmcnt(0)
	s_barrier
	s_setprio 1
	s_waitcnt lgkmcnt(0)
	v_mfma_f32_16x16x32_bf16 v[124:127], v[132:135], v[164:167], v[124:127]
	v_mfma_f32_16x16x32_bf16 v[116:119], v[140:143], v[164:167], v[116:119]
	v_mfma_f32_16x16x32_bf16 v[108:111], v[132:135], v[184:187], v[108:111]
	v_mfma_f32_16x16x32_bf16 v[100:103], v[140:143], v[184:187], v[100:103]
	v_mfma_f32_16x16x32_bf16 v[92:95], v[132:135], v[196:199], v[92:95]
	v_mfma_f32_16x16x32_bf16 v[84:87], v[140:143], v[196:199], v[84:87]
	v_mfma_f32_16x16x32_bf16 v[76:79], v[132:135], v[210:213], v[76:79]
	v_mfma_f32_16x16x32_bf16 v[68:71], v[140:143], v[210:213], v[68:71]
	v_mfma_f32_16x16x32_bf16 v[124:127], v[136:139], v[168:171], v[124:127]
	v_mfma_f32_16x16x32_bf16 v[116:119], v[144:147], v[168:171], v[116:119]
	v_mfma_f32_16x16x32_bf16 v[108:111], v[136:139], v[188:191], v[108:111]
	v_mfma_f32_16x16x32_bf16 v[100:103], v[144:147], v[188:191], v[100:103]
	v_mfma_f32_16x16x32_bf16 v[92:95], v[136:139], v[200:203], v[92:95]
	v_mfma_f32_16x16x32_bf16 v[84:87], v[144:147], v[200:203], v[84:87]
	v_mfma_f32_16x16x32_bf16 v[76:79], v[136:139], v[214:217], v[76:79]
	v_mfma_f32_16x16x32_bf16 v[68:71], v[144:147], v[214:217], v[68:71]
	v_mfma_f32_16x16x32_bf16 v[128:131], v[148:151], v[164:167], v[128:131]
	v_mfma_f32_16x16x32_bf16 v[120:123], v[156:159], v[164:167], v[120:123]
	v_mfma_f32_16x16x32_bf16 v[112:115], v[148:151], v[184:187], v[112:115]
	v_mfma_f32_16x16x32_bf16 v[104:107], v[156:159], v[184:187], v[104:107]
	v_mfma_f32_16x16x32_bf16 v[96:99], v[148:151], v[196:199], v[96:99]
	v_mfma_f32_16x16x32_bf16 v[88:91], v[156:159], v[196:199], v[88:91]
	v_mfma_f32_16x16x32_bf16 v[80:83], v[148:151], v[210:213], v[80:83]
	v_mfma_f32_16x16x32_bf16 v[72:75], v[156:159], v[210:213], v[72:75]
	v_mfma_f32_16x16x32_bf16 v[128:131], v[152:155], v[168:171], v[128:131]
	v_mfma_f32_16x16x32_bf16 v[120:123], v[160:163], v[168:171], v[120:123]
	v_mfma_f32_16x16x32_bf16 v[112:115], v[152:155], v[188:191], v[112:115]
	v_mfma_f32_16x16x32_bf16 v[104:107], v[160:163], v[188:191], v[104:107]
	v_mfma_f32_16x16x32_bf16 v[96:99], v[152:155], v[200:203], v[96:99]
	v_mfma_f32_16x16x32_bf16 v[88:91], v[160:163], v[200:203], v[88:91]
	v_mfma_f32_16x16x32_bf16 v[80:83], v[152:155], v[214:217], v[80:83]
	v_mfma_f32_16x16x32_bf16 v[72:75], v[160:163], v[214:217], v[72:75]
	s_setprio 0
	s_barrier
	s_add_i32 s8, s58, s88
	v_lshl_add_u64 v[6:7], v[192:193], 0, s[96:97]
	s_mov_b32 m0, s8
	ds_read_b128 v[164:167], v208 offset:49152
	ds_read_b128 v[168:171], v208 offset:50176
	ds_read_b128 v[184:187], v208 offset:51200
	ds_read_b128 v[188:191], v208 offset:52224
	ds_read_b128 v[196:199], v208 offset:53248
	ds_read_b128 v[200:203], v208 offset:54272
	ds_read_b128 v[210:213], v208 offset:55296
	ds_read_b128 v[214:217], v208 offset:56320
	global_load_lds_dwordx4 v[6:7], off
	v_lshl_add_u64 v[6:7], v[204:205], 0, s[96:97]
	s_add_i32 m0, s8, 0x2000
	s_add_i32 s8, s59, s88
	global_load_lds_dwordx4 v[6:7], off
	v_lshl_add_u64 v[6:7], v[218:219], 0, s[96:97]
	s_mov_b32 m0, s8
	s_nop 0
	global_load_lds_dwordx4 v[6:7], off
	v_lshl_add_u64 v[6:7], v[220:221], 0, s[96:97]
	s_add_i32 m0, s8, 0x2000
	s_nop 0
	global_load_lds_dwordx4 v[6:7], off
	v_lshl_add_u64 v[6:7], s[0:1], 0, v[176:177]
	s_mov_b32 m0, s93
	s_nop 0
	global_load_lds_dwordx4 v[6:7], off
	v_lshl_add_u64 v[6:7], s[0:1], 0, v[172:173]
	s_mov_b32 m0, s78
	s_nop 0
	global_load_lds_dwordx4 v[6:7], off
	s_waitcnt vmcnt(8)
	s_waitcnt lgkmcnt(0)
	s_barrier
	s_setprio 1
	s_waitcnt lgkmcnt(0)
	v_mfma_f32_16x16x32_bf16 v[60:63], v[132:135], v[164:167], v[60:63]
	v_mfma_f32_16x16x32_bf16 v[52:55], v[140:143], v[164:167], v[52:55]
	v_mfma_f32_16x16x32_bf16 v[44:47], v[132:135], v[184:187], v[44:47]
	v_mfma_f32_16x16x32_bf16 v[36:39], v[140:143], v[184:187], v[36:39]
	v_mfma_f32_16x16x32_bf16 v[28:31], v[132:135], v[196:199], v[28:31]
	v_mfma_f32_16x16x32_bf16 v[20:23], v[140:143], v[196:199], v[20:23]
	v_mfma_f32_16x16x32_bf16 v[12:15], v[132:135], v[210:213], v[12:15]
	v_mfma_f32_16x16x32_bf16 v[2:5], v[140:143], v[210:213], v[2:5]
	v_mfma_f32_16x16x32_bf16 v[60:63], v[136:139], v[168:171], v[60:63]
	v_mfma_f32_16x16x32_bf16 v[52:55], v[144:147], v[168:171], v[52:55]
	v_mfma_f32_16x16x32_bf16 v[44:47], v[136:139], v[188:191], v[44:47]
	v_mfma_f32_16x16x32_bf16 v[36:39], v[144:147], v[188:191], v[36:39]
	v_mfma_f32_16x16x32_bf16 v[28:31], v[136:139], v[200:203], v[28:31]
	v_mfma_f32_16x16x32_bf16 v[20:23], v[144:147], v[200:203], v[20:23]
	v_mfma_f32_16x16x32_bf16 v[12:15], v[136:139], v[214:217], v[12:15]
	v_mfma_f32_16x16x32_bf16 v[4:7], v[144:147], v[214:217], v[2:5]
	v_mfma_f32_16x16x32_bf16 v[64:67], v[148:151], v[164:167], v[64:67]
	v_mfma_f32_16x16x32_bf16 v[56:59], v[156:159], v[164:167], v[56:59]
	v_mfma_f32_16x16x32_bf16 v[48:51], v[148:151], v[184:187], v[48:51]
	v_mfma_f32_16x16x32_bf16 v[40:43], v[156:159], v[184:187], v[40:43]
	v_mfma_f32_16x16x32_bf16 v[32:35], v[148:151], v[196:199], v[32:35]
	v_mfma_f32_16x16x32_bf16 v[24:27], v[156:159], v[196:199], v[24:27]
	v_mfma_f32_16x16x32_bf16 v[16:19], v[148:151], v[210:213], v[16:19]
	v_mfma_f32_16x16x32_bf16 v[8:11], v[156:159], v[210:213], v[8:11]
	v_mfma_f32_16x16x32_bf16 v[64:67], v[152:155], v[168:171], v[64:67]
	v_mfma_f32_16x16x32_bf16 v[56:59], v[160:163], v[168:171], v[56:59]
	v_mfma_f32_16x16x32_bf16 v[48:51], v[152:155], v[188:191], v[48:51]
	v_mfma_f32_16x16x32_bf16 v[40:43], v[160:163], v[188:191], v[40:43]
	v_mfma_f32_16x16x32_bf16 v[32:35], v[152:155], v[200:203], v[32:35]
	v_mfma_f32_16x16x32_bf16 v[24:27], v[160:163], v[200:203], v[24:27]
	v_mfma_f32_16x16x32_bf16 v[16:19], v[152:155], v[214:217], v[16:19]
	v_mfma_f32_16x16x32_bf16 v[8:11], v[160:163], v[214:217], v[8:11]
	s_setprio 0
	s_barrier
	s_add_u32 s6, s6, 0x100
	s_addc_u32 s7, s7, 0
	s_add_u32 s54, s54, 0x100
	s_addc_u32 s55, s55, 0
	s_add_i32 s56, s56, -2
	s_cmp_ge_u32 s57, s18
	s_mov_b32 s0, s57
	s_cbranch_scc0 .LBB0_1180
